# GEMM MFMA issue order: same accumulator back to back (k0,k1) and snake over k, n, m so each MFMA shares the accumulator or an A/B fragment with its predecessor
# speedup vs baseline: 1.0083x; 1.0083x over previous
; #define PG8_STAGE(bufoff, gbase, voff) do { _Pragma("unroll") for (int _i = 0; _i < 2; ++_i) \
;         __builtin_amdgcn_global_load_lds((const unsigned*)((const char*)(gbase) + (voff)[_i]), (PG8_LAS unsigned*)(lds + (bufoff) + ldsw + _i * 8192), 16, 0, 0); } while (0)
; #define PG8_LDA(dst, b, h) do { _Pragma("unroll") for (int m = 0; m < 4; ++m) _Pragma("unroll") for (int k = 0; k < 2; ++k) dst[m][k] = *(const PG8_LAS bf16x8*)(lds + PG8_SA(b, h) + aoff + m * 2048 + k * 1024); } while (0)
; #define PG8_LDB(dst, b, h) do { _Pragma("unroll") for (int n = 0; n < 2; ++n) _Pragma("unroll") for (int k = 0; k < 2; ++k) dst[n][k] = *(const PG8_LAS bf16x8*)(lds + PG8_SB(b, h) + boff + n * 2048 + k * 1024); } while (0)
; #define PG8_MMA(ai, bj, At, Bt) do { __builtin_amdgcn_s_setprio(1); _Pragma("unroll") for (int m = 0; m < 4; ++m) _Pragma("unroll") for (int n = 0; n < 2; ++n) _Pragma("unroll") for (int k = 0; k < 2; ++k) \
;         acc[ai][bj][m][n] = __builtin_amdgcn_mfma_f32_16x16x32_bf16(Bt[n][k], At[m][k], acc[ai][bj][m][n], 0, 0, 0); __builtin_amdgcn_s_setprio(0); } while (0)
; #define PG8_WAIT_V(n) asm volatile("s_waitcnt vmcnt(" #n ")" ::: "memory")
; #define PG8_WAIT_L(n) asm volatile("s_waitcnt lgkmcnt(" #n ")" ::: "memory")
; #define PG8_BAR __builtin_amdgcn_s_barrier()
; template <class Epi, class Sched, bool ALIGN_EPI = false, bool SP2 = false, class Hook = NoHook, bool REVK = false>
; __device__ __forceinline__ void gemm_phase(PG8_LAS unsigned char* lds, const Gemm g, const Sched& S, const Epi& E, const Hook H = Hook()) {
;     ...
;             const char* a2 = last ? nA : cA + (long)(t + 2) * kstep; const char* b2 = last ? nB : cB + (long)(t + 2) * kstep;
;             const char* a3 = a2 + kstep; const char* b3 = b2 + kstep;
;             if (last && has_next) S.a_ready(nxt);
;             if constexpr (SP2) {
;             PG8_LDB(B0, 0, 0); PG8_LDB(B1, 0, 1); PG8_SCHED; PG8_LDA(At, 0, 0); PG8_STAGE(PG8_SA(1, 1), a1 + hstep, voffA);
;             PG8_WAIT_V(8); PG8_WAIT_L(0); PG8_BAR; PG8_MMA(0, 0, At, B0); PG8_MMA(0, 1, At, B1); PG8_BAR; PG8_SCHED;
;             PG8_LDA(At, 0, 1); PG8_STAGE(PG8_SB(0, 0), b2, voffB); PG8_STAGE(PG8_SB(0, 1), b2 + hstep, voffB); PG8_STAGE(PG8_SA(0, 0), a2, voffA);
;             PG8_WAIT_V(8); PG8_WAIT_L(0); PG8_BAR; PG8_MMA(1, 0, At, B0); PG8_MMA(1, 1, At, B1); PG8_BAR; PG8_SCHED;
.LBB0_58:
	s_ashr_i32 s93, s92, 31
	s_lshl_b64 s[22:23], s[92:93], 20
	s_add_u32 s94, s39, s22
	s_addc_u32 s95, s40, s23
	s_and_b64 s[22:23], s[6:7], exec
	s_cselect_b32 s29, s95, s27
	s_cselect_b32 s30, s94, s26
	s_ashr_i32 s91, s90, 31
	s_lshl_b64 s[22:23], s[90:91], 20
	s_add_u32 s96, s41, s22
	s_addc_u32 s97, s42, s23
	s_and_b64 s[22:23], s[6:7], exec
	s_cselect_b32 s31, s97, s21
	s_cselect_b32 s91, s96, s20
	s_add_u32 s22, s26, 0x80080
	s_addc_u32 s23, s27, 0
	s_add_u32 s93, s20, 0x100
	s_addc_u32 s98, s21, 0
	s_mov_b32 s99, -2
	s_waitcnt vmcnt(0)
	s_add_u32 s20, s22, 0xfff80080
	s_addc_u32 s21, s23, -1
	s_add_i32 s46, 0, 0x10000
	s_cmp_eq_u32 s99, 28
	s_cselect_b32 s27, s29, s21
	s_cselect_b32 s26, s30, s20
	s_cselect_b32 s21, s31, s98
	s_cselect_b32 s20, s91, s93
	s_add_i32 s58, 0, 0x14000
	v_add_u32_e32 v108, s46, v164
	v_add_u32_e32 v128, s58, v164
	ds_read_b128 v[96:99], v108
	ds_read_b128 v[100:103], v108 offset:1024
	ds_read_b128 v[104:107], v108 offset:2048
	ds_read_b128 v[108:111], v108 offset:3072
	ds_read_b128 v[182:185], v128
	ds_read_b128 v[186:189], v128 offset:1024
	ds_read_b128 v[190:193], v128 offset:2048
	ds_read_b128 v[194:197], v128 offset:3072
	v_lshl_add_u64 v[162:163], s[22:23], 0, v[158:159]
	s_add_i32 m0, s43, 0xc000
	ds_read_b128 v[200:203], v167
	ds_read_b128 v[204:207], v167 offset:1024
	ds_read_b128 v[210:213], v167 offset:2048
	ds_read_b128 v[226:229], v167 offset:3072
	ds_read_b128 v[230:233], v167 offset:4096
	ds_read_b128 v[234:237], v167 offset:5120
	ds_read_b128 v[238:241], v167 offset:6144
	ds_read_b128 v[242:245], v167 offset:7168
	global_load_lds_dwordx4 v[162:163], off
	v_lshl_add_u64 v[162:163], s[22:23], 0, v[160:161]
	s_add_i32 m0, s43, 0xe000
	s_nop 0
	global_load_lds_dwordx4 v[162:163], off
	s_waitcnt vmcnt(8)
	s_waitcnt lgkmcnt(0)
	s_setprio 1
	s_barrier
	v_mfma_f32_16x16x32_bf16 v[142:145], v[96:99], v[200:203], 0
	v_mfma_f32_16x16x32_bf16 v[142:145], v[100:103], v[204:207], v[142:145]
	v_mfma_f32_16x16x32_bf16 v[138:141], v[108:111], v[204:207], 0
	v_mfma_f32_16x16x32_bf16 v[138:141], v[104:107], v[200:203], v[138:141]
	v_mfma_f32_16x16x32_bf16 v[130:133], v[182:185], v[200:203], 0
	v_mfma_f32_16x16x32_bf16 v[130:133], v[186:189], v[204:207], v[130:133]
	v_mfma_f32_16x16x32_bf16 v[134:137], v[194:197], v[204:207], 0
	v_mfma_f32_16x16x32_bf16 v[134:137], v[190:193], v[200:203], v[134:137]
	v_mfma_f32_16x16x32_bf16 v[124:127], v[190:193], v[210:213], 0
	v_mfma_f32_16x16x32_bf16 v[124:127], v[194:197], v[226:229], v[124:127]
	v_mfma_f32_16x16x32_bf16 v[112:115], v[186:189], v[226:229], 0
	v_mfma_f32_16x16x32_bf16 v[112:115], v[182:185], v[210:213], v[112:115]
	v_mfma_f32_16x16x32_bf16 v[120:123], v[104:107], v[210:213], 0
	v_mfma_f32_16x16x32_bf16 v[120:123], v[108:111], v[226:229], v[120:123]
	v_mfma_f32_16x16x32_bf16 v[116:119], v[100:103], v[226:229], 0
	v_mfma_f32_16x16x32_bf16 v[116:119], v[96:99], v[210:213], v[116:119]
	v_mfma_f32_16x16x32_bf16 v[84:87], v[96:99], v[230:233], 0
	v_mfma_f32_16x16x32_bf16 v[84:87], v[100:103], v[234:237], v[84:87]
	v_mfma_f32_16x16x32_bf16 v[88:91], v[108:111], v[234:237], 0
	v_mfma_f32_16x16x32_bf16 v[88:91], v[104:107], v[230:233], v[88:91]
	v_mfma_f32_16x16x32_bf16 v[80:83], v[182:185], v[230:233], 0
	v_mfma_f32_16x16x32_bf16 v[80:83], v[186:189], v[234:237], v[80:83]
	v_mfma_f32_16x16x32_bf16 v[92:95], v[194:197], v[234:237], 0
	v_mfma_f32_16x16x32_bf16 v[92:95], v[190:193], v[230:233], v[92:95]
	v_mfma_f32_16x16x32_bf16 v[76:79], v[190:193], v[238:241], 0
	v_mfma_f32_16x16x32_bf16 v[76:79], v[194:197], v[242:245], v[76:79]
	v_mfma_f32_16x16x32_bf16 v[64:67], v[186:189], v[242:245], 0
	v_mfma_f32_16x16x32_bf16 v[64:67], v[182:185], v[238:241], v[64:67]
	v_mfma_f32_16x16x32_bf16 v[72:75], v[104:107], v[238:241], 0
	v_mfma_f32_16x16x32_bf16 v[72:75], v[108:111], v[242:245], v[72:75]
	v_mfma_f32_16x16x32_bf16 v[68:71], v[100:103], v[242:245], 0
	v_mfma_f32_16x16x32_bf16 v[68:71], v[96:99], v[238:241], v[68:71]
	s_barrier
	s_setprio 0
	s_add_i32 s46, s46, s38
	v_lshl_add_u64 v[162:163], s[20:21], 0, v[150:151]
	s_mov_b32 m0, s46
	ds_read_b128 v[200:203], v167 offset:16384
	ds_read_b128 v[204:207], v167 offset:17408
	ds_read_b128 v[210:213], v167 offset:18432
	ds_read_b128 v[226:229], v167 offset:19456
	ds_read_b128 v[230:233], v167 offset:20480
	ds_read_b128 v[234:237], v167 offset:21504
	ds_read_b128 v[238:241], v167 offset:22528
	ds_read_b128 v[242:245], v167 offset:23552
	global_load_lds_dwordx4 v[162:163], off
	s_add_i32 m0, s46, 0x2000
	s_add_u32 s56, s20, 0x80000
	v_lshl_add_u64 v[168:169], s[20:21], 0, v[146:147]
	s_addc_u32 s57, s21, 0
	s_add_i32 s46, s58, s38
	global_load_lds_dwordx4 v[168:169], off
	v_lshl_add_u64 v[214:215], s[56:57], 0, v[150:151]
	s_mov_b32 m0, s46
	v_lshl_add_u64 v[246:247], s[26:27], 0, v[148:149]
	global_load_lds_dwordx4 v[214:215], off
	v_lshl_add_u64 v[214:215], s[56:57], 0, v[146:147]
	s_add_i32 m0, s46, 0x2000
	s_nop 0
	global_load_lds_dwordx4 v[214:215], off
	v_lshl_add_u64 v[214:215], s[26:27], 0, v[152:153]
	s_mov_b32 m0, s43
	s_nop 0
	global_load_lds_dwordx4 v[214:215], off
	s_mov_b32 m0, s75
	s_nop 0
	global_load_lds_dwordx4 v[246:247], off
	s_waitcnt vmcnt(8)
	s_waitcnt lgkmcnt(0)
	s_setprio 1
	s_barrier
; #define PG8_STAGE(bufoff, gbase, voff) do { _Pragma("unroll") for (int _i = 0; _i < 2; ++_i) \
;         __builtin_amdgcn_global_load_lds((const unsigned*)((const char*)(gbase) + (voff)[_i]), (PG8_LAS unsigned*)(lds + (bufoff) + ldsw + _i * 8192), 16, 0, 0); } while (0)
; #define PG8_LDA(dst, b, h) do { _Pragma("unroll") for (int m = 0; m < 4; ++m) _Pragma("unroll") for (int k = 0; k < 2; ++k) dst[m][k] = *(const PG8_LAS bf16x8*)(lds + PG8_SA(b, h) + aoff + m * 2048 + k * 1024); } while (0)
; #define PG8_LDB(dst, b, h) do { _Pragma("unroll") for (int n = 0; n < 2; ++n) _Pragma("unroll") for (int k = 0; k < 2; ++k) dst[n][k] = *(const PG8_LAS bf16x8*)(lds + PG8_SB(b, h) + boff + n * 2048 + k * 1024); } while (0)
; #define PG8_MMA(ai, bj, At, Bt) do { __builtin_amdgcn_s_setprio(1); _Pragma("unroll") for (int m = 0; m < 4; ++m) _Pragma("unroll") for (int n = 0; n < 2; ++n) _Pragma("unroll") for (int k = 0; k < 2; ++k) \
;         acc[ai][bj][m][n] = __builtin_amdgcn_mfma_f32_16x16x32_bf16(Bt[n][k], At[m][k], acc[ai][bj][m][n], 0, 0, 0); __builtin_amdgcn_s_setprio(0); } while (0)
; #define PG8_WAIT_V(n) asm volatile("s_waitcnt vmcnt(" #n ")" ::: "memory")
; #define PG8_WAIT_L(n) asm volatile("s_waitcnt lgkmcnt(" #n ")" ::: "memory")
; #define PG8_BAR __builtin_amdgcn_s_barrier()
; #define PG8_SCHED __builtin_amdgcn_sched_barrier(0)
; template <class Epi, class Sched, bool ALIGN_EPI = false, bool SP2 = false, class Hook = NoHook, bool REVK = false>
; __device__ __forceinline__ void gemm_phase(PG8_LAS unsigned char* lds, const Gemm g, const Sched& S, const Epi& E, const Hook H = Hook()) {
;     ...
;             PG8_WAIT_V(8); PG8_WAIT_L(0); PG8_BAR; PG8_MMA(1, 0, At, B0); PG8_MMA(1, 1, At, B1); PG8_BAR; PG8_SCHED;
;             PG8_LDB(B0, 1, 0); PG8_LDB(B1, 1, 1); PG8_SCHED; PG8_LDA(At, 1, 0); PG8_STAGE(PG8_SA(0, 1), a2 + hstep, voffA);
;             PG8_WAIT_V(8); PG8_WAIT_L(0); PG8_BAR; PG8_MMA(0, 0, At, B0); PG8_MMA(0, 1, At, B1); PG8_BAR; PG8_SCHED;
	v_mfma_f32_16x16x32_bf16 v[52:55], v[96:99], v[200:203], 0
	v_mfma_f32_16x16x32_bf16 v[52:55], v[100:103], v[204:207], v[52:55]
	v_mfma_f32_16x16x32_bf16 v[56:59], v[108:111], v[204:207], 0
	v_mfma_f32_16x16x32_bf16 v[56:59], v[104:107], v[200:203], v[56:59]
	v_mfma_f32_16x16x32_bf16 v[48:51], v[182:185], v[200:203], 0
	v_mfma_f32_16x16x32_bf16 v[48:51], v[186:189], v[204:207], v[48:51]
	v_mfma_f32_16x16x32_bf16 v[60:63], v[194:197], v[204:207], 0
	v_mfma_f32_16x16x32_bf16 v[60:63], v[190:193], v[200:203], v[60:63]
	v_mfma_f32_16x16x32_bf16 v[44:47], v[190:193], v[210:213], 0
	v_mfma_f32_16x16x32_bf16 v[44:47], v[194:197], v[226:229], v[44:47]
	v_mfma_f32_16x16x32_bf16 v[32:35], v[186:189], v[226:229], 0
	v_mfma_f32_16x16x32_bf16 v[32:35], v[182:185], v[210:213], v[32:35]
	v_mfma_f32_16x16x32_bf16 v[40:43], v[104:107], v[210:213], 0
	v_mfma_f32_16x16x32_bf16 v[40:43], v[108:111], v[226:229], v[40:43]
	v_mfma_f32_16x16x32_bf16 v[36:39], v[100:103], v[226:229], 0
	v_mfma_f32_16x16x32_bf16 v[36:39], v[96:99], v[210:213], v[36:39]
	v_mfma_f32_16x16x32_bf16 v[20:23], v[96:99], v[230:233], 0
	v_mfma_f32_16x16x32_bf16 v[20:23], v[100:103], v[234:237], v[20:23]
	v_mfma_f32_16x16x32_bf16 v[24:27], v[108:111], v[234:237], 0
	v_mfma_f32_16x16x32_bf16 v[24:27], v[104:107], v[230:233], v[24:27]
	v_mfma_f32_16x16x32_bf16 v[16:19], v[182:185], v[230:233], 0
	v_mfma_f32_16x16x32_bf16 v[16:19], v[186:189], v[234:237], v[16:19]
	v_mfma_f32_16x16x32_bf16 v[28:31], v[194:197], v[234:237], 0
	v_mfma_f32_16x16x32_bf16 v[28:31], v[190:193], v[230:233], v[28:31]
	v_mfma_f32_16x16x32_bf16 v[12:15], v[190:193], v[238:241], 0
	v_mfma_f32_16x16x32_bf16 v[12:15], v[194:197], v[242:245], v[12:15]
	v_mfma_f32_16x16x32_bf16 v[0:3], v[186:189], v[242:245], 0
	v_mfma_f32_16x16x32_bf16 v[0:3], v[182:185], v[238:241], v[0:3]
	v_mfma_f32_16x16x32_bf16 v[8:11], v[104:107], v[238:241], 0
	v_mfma_f32_16x16x32_bf16 v[8:11], v[108:111], v[242:245], v[8:11]
	v_mfma_f32_16x16x32_bf16 v[4:7], v[100:103], v[242:245], 0
	v_mfma_f32_16x16x32_bf16 v[4:7], v[96:99], v[238:241], v[4:7]
	s_barrier
	s_setprio 0
	s_add_i32 s46, 0, 0x18000
	s_add_i32 s56, 0, 0x1c000
	v_add_u32_e32 v108, s46, v164
	v_add_u32_e32 v128, s56, v164
	ds_read_b128 v[96:99], v108
	ds_read_b128 v[100:103], v108 offset:1024
	ds_read_b128 v[104:107], v108 offset:2048
	ds_read_b128 v[108:111], v108 offset:3072
	ds_read_b128 v[182:185], v128
	ds_read_b128 v[186:189], v128 offset:1024
	ds_read_b128 v[190:193], v128 offset:2048
	ds_read_b128 v[194:197], v128 offset:3072
	s_add_u32 s26, s26, 0x80000
	s_addc_u32 s27, s27, 0
	s_mov_b32 m0, s77
	v_lshl_add_u64 v[248:249], s[26:27], 0, v[152:153]
	ds_read_b128 v[200:203], v167 offset:32768
	ds_read_b128 v[204:207], v167 offset:33792
	ds_read_b128 v[210:213], v167 offset:34816
	ds_read_b128 v[226:229], v167 offset:35840
	ds_read_b128 v[230:233], v167 offset:36864
	ds_read_b128 v[234:237], v167 offset:37888
	ds_read_b128 v[238:241], v167 offset:38912
	ds_read_b128 v[242:245], v167 offset:39936
	global_load_lds_dwordx4 v[248:249], off
	v_lshl_add_u64 v[248:249], s[26:27], 0, v[148:149]
	s_mov_b32 m0, s79
	s_nop 0
	global_load_lds_dwordx4 v[248:249], off
	s_waitcnt vmcnt(8)
	s_waitcnt lgkmcnt(0)
	s_setprio 1
	s_barrier
	v_mfma_f32_16x16x32_bf16 v[142:145], v[96:99], v[200:203], v[142:145]
	v_mfma_f32_16x16x32_bf16 v[142:145], v[100:103], v[204:207], v[142:145]
	v_mfma_f32_16x16x32_bf16 v[138:141], v[108:111], v[204:207], v[138:141]
	v_mfma_f32_16x16x32_bf16 v[138:141], v[104:107], v[200:203], v[138:141]
	v_mfma_f32_16x16x32_bf16 v[130:133], v[182:185], v[200:203], v[130:133]
	v_mfma_f32_16x16x32_bf16 v[130:133], v[186:189], v[204:207], v[130:133]
	v_mfma_f32_16x16x32_bf16 v[134:137], v[194:197], v[204:207], v[134:137]
	v_mfma_f32_16x16x32_bf16 v[134:137], v[190:193], v[200:203], v[134:137]
	v_mfma_f32_16x16x32_bf16 v[124:127], v[190:193], v[210:213], v[124:127]
	v_mfma_f32_16x16x32_bf16 v[124:127], v[194:197], v[226:229], v[124:127]
	v_mfma_f32_16x16x32_bf16 v[112:115], v[186:189], v[226:229], v[112:115]
	v_mfma_f32_16x16x32_bf16 v[112:115], v[182:185], v[210:213], v[112:115]
	v_mfma_f32_16x16x32_bf16 v[120:123], v[104:107], v[210:213], v[120:123]
	v_mfma_f32_16x16x32_bf16 v[120:123], v[108:111], v[226:229], v[120:123]
	v_mfma_f32_16x16x32_bf16 v[116:119], v[100:103], v[226:229], v[116:119]
	v_mfma_f32_16x16x32_bf16 v[116:119], v[96:99], v[210:213], v[116:119]
	v_mfma_f32_16x16x32_bf16 v[84:87], v[96:99], v[230:233], v[84:87]
	v_mfma_f32_16x16x32_bf16 v[84:87], v[100:103], v[234:237], v[84:87]
	v_mfma_f32_16x16x32_bf16 v[88:91], v[108:111], v[234:237], v[88:91]
	v_mfma_f32_16x16x32_bf16 v[88:91], v[104:107], v[230:233], v[88:91]
	v_mfma_f32_16x16x32_bf16 v[80:83], v[182:185], v[230:233], v[80:83]
	v_mfma_f32_16x16x32_bf16 v[80:83], v[186:189], v[234:237], v[80:83]
	v_mfma_f32_16x16x32_bf16 v[92:95], v[194:197], v[234:237], v[92:95]
	v_mfma_f32_16x16x32_bf16 v[92:95], v[190:193], v[230:233], v[92:95]
	v_mfma_f32_16x16x32_bf16 v[76:79], v[190:193], v[238:241], v[76:79]
	v_mfma_f32_16x16x32_bf16 v[76:79], v[194:197], v[242:245], v[76:79]
	v_mfma_f32_16x16x32_bf16 v[64:67], v[186:189], v[242:245], v[64:67]
	v_mfma_f32_16x16x32_bf16 v[64:67], v[182:185], v[238:241], v[64:67]
	v_mfma_f32_16x16x32_bf16 v[72:75], v[104:107], v[238:241], v[72:75]
	v_mfma_f32_16x16x32_bf16 v[72:75], v[108:111], v[242:245], v[72:75]
	v_mfma_f32_16x16x32_bf16 v[68:71], v[100:103], v[242:245], v[68:71]
	v_mfma_f32_16x16x32_bf16 v[68:71], v[96:99], v[238:241], v[68:71]
	s_barrier
; #define PG8_STAGE(bufoff, gbase, voff) do { _Pragma("unroll") for (int _i = 0; _i < 2; ++_i) \
;         __builtin_amdgcn_global_load_lds((const unsigned*)((const char*)(gbase) + (voff)[_i]), (PG8_LAS unsigned*)(lds + (bufoff) + ldsw + _i * 8192), 16, 0, 0); } while (0)
; #define PG8_LDA(dst, b, h) do { _Pragma("unroll") for (int m = 0; m < 4; ++m) _Pragma("unroll") for (int k = 0; k < 2; ++k) dst[m][k] = *(const PG8_LAS bf16x8*)(lds + PG8_SA(b, h) + aoff + m * 2048 + k * 1024); } while (0)
; #define PG8_LDB(dst, b, h) do { _Pragma("unroll") for (int n = 0; n < 2; ++n) _Pragma("unroll") for (int k = 0; k < 2; ++k) dst[n][k] = *(const PG8_LAS bf16x8*)(lds + PG8_SB(b, h) + boff + n * 2048 + k * 1024); } while (0)
; #define PG8_WAIT_V(n) asm volatile("s_waitcnt vmcnt(" #n ")" ::: "memory")
; #define PG8_WAIT_L(n) asm volatile("s_waitcnt lgkmcnt(" #n ")" ::: "memory")
; #define PG8_BAR __builtin_amdgcn_s_barrier()
; template <class Epi, class Sched, bool ALIGN_EPI = false, bool SP2 = false, class Hook = NoHook, bool REVK = false>
; __device__ __forceinline__ void gemm_phase(PG8_LAS unsigned char* lds, const Gemm g, const Sched& S, const Epi& E, const Hook H = Hook()) {
;     ...
;         for (int t = 0; t < nt; t += 2) {
;             if constexpr (Hook::ENABLED) H(acc, t, nt, ui, wr, fr);
;             const bool last = (t == nt - 2);
;             const char* a1 = cA + (long)(t + 1) * kstep;
;             const char* a2 = last ? nA : cA + (long)(t + 2) * kstep; const char* b2 = last ? nB : cB + (long)(t + 2) * kstep;
;             const char* a3 = a2 + kstep; const char* b3 = b2 + kstep;
;             if (last && has_next) S.a_ready(nxt);
;             if constexpr (SP2) {
;             PG8_LDB(B0, 0, 0); PG8_LDB(B1, 0, 1); PG8_SCHED; PG8_LDA(At, 0, 0); PG8_STAGE(PG8_SA(1, 1), a1 + hstep, voffA);
;             PG8_WAIT_V(8); PG8_WAIT_L(0); PG8_BAR; PG8_MMA(0, 0, At, B0); PG8_MMA(0, 1, At, B1); PG8_BAR; PG8_SCHED;
;             PG8_LDA(At, 0, 1); PG8_STAGE(PG8_SB(0, 0), b2, voffB); PG8_STAGE(PG8_SB(0, 1), b2 + hstep, voffB); PG8_STAGE(PG8_SA(0, 0), a2, voffA);
;     ...
;             PG8_LDA(At, 1, 1); PG8_STAGE(PG8_SB(1, 0), b3, voffB); PG8_STAGE(PG8_SB(1, 1), b3 + hstep, voffB); PG8_STAGE(PG8_SA(1, 0), a3, voffA);
;             PG8_WAIT_V(8); PG8_WAIT_L(0); PG8_BAR; PG8_MMA(1, 0, At, B0); PG8_MMA(1, 1, At, B1); PG8_BAR; PG8_SCHED;
	s_setprio 0
	s_add_i32 s26, s46, s38
	v_lshl_add_u64 v[162:163], v[162:163], 0, s[64:65]
	s_mov_b32 m0, s26
	ds_read_b128 v[200:203], v167 offset:49152
	ds_read_b128 v[204:207], v167 offset:50176
	ds_read_b128 v[210:213], v167 offset:51200
	ds_read_b128 v[226:229], v167 offset:52224
	ds_read_b128 v[230:233], v167 offset:53248
	ds_read_b128 v[234:237], v167 offset:54272
	ds_read_b128 v[238:241], v167 offset:55296
	ds_read_b128 v[242:245], v167 offset:56320
	global_load_lds_dwordx4 v[162:163], off
	s_add_i32 m0, s26, 0x2000
	s_add_u32 s20, s20, 0x80080
	v_lshl_add_u64 v[162:163], v[168:169], 0, s[64:65]
	s_addc_u32 s21, s21, 0
	s_add_i32 s26, s56, s38
	global_load_lds_dwordx4 v[162:163], off
	v_lshl_add_u64 v[162:163], s[20:21], 0, v[150:151]
	s_mov_b32 m0, s26
	s_nop 0
	global_load_lds_dwordx4 v[162:163], off
	v_lshl_add_u64 v[162:163], s[20:21], 0, v[146:147]
	s_add_i32 m0, s26, 0x2000
	s_nop 0
	global_load_lds_dwordx4 v[162:163], off
	v_lshl_add_u64 v[162:163], v[214:215], 0, s[64:65]
	s_mov_b32 m0, s44
	s_nop 0
	global_load_lds_dwordx4 v[162:163], off
	v_lshl_add_u64 v[162:163], v[246:247], 0, s[64:65]
	s_mov_b32 m0, s36
	s_nop 0
	global_load_lds_dwordx4 v[162:163], off
	s_waitcnt vmcnt(8)
	s_waitcnt lgkmcnt(0)
	s_setprio 1
	s_barrier
	v_mfma_f32_16x16x32_bf16 v[52:55], v[96:99], v[200:203], v[52:55]
	v_mfma_f32_16x16x32_bf16 v[52:55], v[100:103], v[204:207], v[52:55]
	v_mfma_f32_16x16x32_bf16 v[56:59], v[108:111], v[204:207], v[56:59]
	v_mfma_f32_16x16x32_bf16 v[56:59], v[104:107], v[200:203], v[56:59]
	v_mfma_f32_16x16x32_bf16 v[48:51], v[182:185], v[200:203], v[48:51]
	v_mfma_f32_16x16x32_bf16 v[48:51], v[186:189], v[204:207], v[48:51]
	v_mfma_f32_16x16x32_bf16 v[60:63], v[194:197], v[204:207], v[60:63]
	v_mfma_f32_16x16x32_bf16 v[60:63], v[190:193], v[200:203], v[60:63]
	v_mfma_f32_16x16x32_bf16 v[44:47], v[190:193], v[210:213], v[44:47]
	v_mfma_f32_16x16x32_bf16 v[44:47], v[194:197], v[226:229], v[44:47]
	v_mfma_f32_16x16x32_bf16 v[32:35], v[186:189], v[226:229], v[32:35]
	v_mfma_f32_16x16x32_bf16 v[32:35], v[182:185], v[210:213], v[32:35]
	v_mfma_f32_16x16x32_bf16 v[40:43], v[104:107], v[210:213], v[40:43]
	v_mfma_f32_16x16x32_bf16 v[40:43], v[108:111], v[226:229], v[40:43]
	v_mfma_f32_16x16x32_bf16 v[36:39], v[100:103], v[226:229], v[36:39]
	v_mfma_f32_16x16x32_bf16 v[36:39], v[96:99], v[210:213], v[36:39]
	v_mfma_f32_16x16x32_bf16 v[20:23], v[96:99], v[230:233], v[20:23]
	v_mfma_f32_16x16x32_bf16 v[20:23], v[100:103], v[234:237], v[20:23]
	v_mfma_f32_16x16x32_bf16 v[24:27], v[108:111], v[234:237], v[24:27]
	v_mfma_f32_16x16x32_bf16 v[24:27], v[104:107], v[230:233], v[24:27]
	v_mfma_f32_16x16x32_bf16 v[16:19], v[182:185], v[230:233], v[16:19]
	v_mfma_f32_16x16x32_bf16 v[16:19], v[186:189], v[234:237], v[16:19]
	v_mfma_f32_16x16x32_bf16 v[28:31], v[194:197], v[234:237], v[28:31]
	v_mfma_f32_16x16x32_bf16 v[28:31], v[190:193], v[230:233], v[28:31]
	v_mfma_f32_16x16x32_bf16 v[12:15], v[190:193], v[238:241], v[12:15]
	v_mfma_f32_16x16x32_bf16 v[12:15], v[194:197], v[242:245], v[12:15]
	v_mfma_f32_16x16x32_bf16 v[0:3], v[186:189], v[242:245], v[0:3]
	v_mfma_f32_16x16x32_bf16 v[0:3], v[182:185], v[238:241], v[0:3]
	v_mfma_f32_16x16x32_bf16 v[8:11], v[104:107], v[238:241], v[8:11]
	v_mfma_f32_16x16x32_bf16 v[8:11], v[108:111], v[242:245], v[8:11]
	v_mfma_f32_16x16x32_bf16 v[4:7], v[100:103], v[242:245], v[4:7]
	v_mfma_f32_16x16x32_bf16 v[4:7], v[96:99], v[238:241], v[4:7]
	s_barrier
	s_setprio 0
	s_add_i32 s99, s99, 2
	s_add_u32 s22, s22, 0x100
	s_addc_u32 s23, s23, 0
	s_add_u32 s93, s93, 0x100
	s_addc_u32 s98, s98, 0
	s_cmp_gt_u32 s99, 29
.LBB0_59:
	s_add_u32 s20, s22, 0xfff80080
	s_addc_u32 s21, s23, -1
	s_add_i32 s46, 0, 0x10000
	s_cmp_eq_u32 s99, 28
	s_cselect_b32 s27, s29, s21
	s_cselect_b32 s26, s30, s20
	s_cselect_b32 s21, s31, s98
	s_cselect_b32 s20, s91, s93
	s_add_i32 s58, 0, 0x14000
	v_add_u32_e32 v108, s46, v164
	v_add_u32_e32 v128, s58, v164
	ds_read_b128 v[96:99], v108
	ds_read_b128 v[100:103], v108 offset:1024
	ds_read_b128 v[104:107], v108 offset:2048
	ds_read_b128 v[108:111], v108 offset:3072
	ds_read_b128 v[182:185], v128
	ds_read_b128 v[186:189], v128 offset:1024
	ds_read_b128 v[190:193], v128 offset:2048
	ds_read_b128 v[194:197], v128 offset:3072
	v_lshl_add_u64 v[162:163], s[22:23], 0, v[158:159]
	s_add_i32 m0, s43, 0xc000
	ds_read_b128 v[200:203], v167
	ds_read_b128 v[204:207], v167 offset:1024
	ds_read_b128 v[210:213], v167 offset:2048
	ds_read_b128 v[226:229], v167 offset:3072
	ds_read_b128 v[230:233], v167 offset:4096
	ds_read_b128 v[234:237], v167 offset:5120
	ds_read_b128 v[238:241], v167 offset:6144
	ds_read_b128 v[242:245], v167 offset:7168
	global_load_lds_dwordx4 v[162:163], off
	v_lshl_add_u64 v[162:163], s[22:23], 0, v[160:161]
	s_add_i32 m0, s43, 0xe000
	s_nop 0
	global_load_lds_dwordx4 v[162:163], off
	s_waitcnt vmcnt(8)
	s_waitcnt lgkmcnt(0)
	s_setprio 1
	s_barrier
; #define PG8_STAGE(bufoff, gbase, voff) do { _Pragma("unroll") for (int _i = 0; _i < 2; ++_i) \
;         __builtin_amdgcn_global_load_lds((const unsigned*)((const char*)(gbase) + (voff)[_i]), (PG8_LAS unsigned*)(lds + (bufoff) + ldsw + _i * 8192), 16, 0, 0); } while (0)
; #define PG8_LDA(dst, b, h) do { _Pragma("unroll") for (int m = 0; m < 4; ++m) _Pragma("unroll") for (int k = 0; k < 2; ++k) dst[m][k] = *(const PG8_LAS bf16x8*)(lds + PG8_SA(b, h) + aoff + m * 2048 + k * 1024); } while (0)
; #define PG8_LDB(dst, b, h) do { _Pragma("unroll") for (int n = 0; n < 2; ++n) _Pragma("unroll") for (int k = 0; k < 2; ++k) dst[n][k] = *(const PG8_LAS bf16x8*)(lds + PG8_SB(b, h) + boff + n * 2048 + k * 1024); } while (0)
; #define PG8_MMA(ai, bj, At, Bt) do { __builtin_amdgcn_s_setprio(1); _Pragma("unroll") for (int m = 0; m < 4; ++m) _Pragma("unroll") for (int n = 0; n < 2; ++n) _Pragma("unroll") for (int k = 0; k < 2; ++k) \
;         acc[ai][bj][m][n] = __builtin_amdgcn_mfma_f32_16x16x32_bf16(Bt[n][k], At[m][k], acc[ai][bj][m][n], 0, 0, 0); __builtin_amdgcn_s_setprio(0); } while (0)
; #define PG8_WAIT_V(n) asm volatile("s_waitcnt vmcnt(" #n ")" ::: "memory")
; #define PG8_WAIT_L(n) asm volatile("s_waitcnt lgkmcnt(" #n ")" ::: "memory")
; #define PG8_BAR __builtin_amdgcn_s_barrier()
; #define PG8_SCHED __builtin_amdgcn_sched_barrier(0)
; template <class Epi, class Sched, bool ALIGN_EPI = false, bool SP2 = false, class Hook = NoHook, bool REVK = false>
; __device__ __forceinline__ void gemm_phase(PG8_LAS unsigned char* lds, const Gemm g, const Sched& S, const Epi& E, const Hook H = Hook()) {
;     ...
;             PG8_LDB(B0, 0, 0); PG8_LDB(B1, 0, 1); PG8_SCHED; PG8_LDA(At, 0, 0); PG8_STAGE(PG8_SA(1, 1), a1 + hstep, voffA);
;             PG8_WAIT_V(8); PG8_WAIT_L(0); PG8_BAR; PG8_MMA(0, 0, At, B0); PG8_MMA(0, 1, At, B1); PG8_BAR; PG8_SCHED;
;             PG8_LDA(At, 0, 1); PG8_STAGE(PG8_SB(0, 0), b2, voffB); PG8_STAGE(PG8_SB(0, 1), b2 + hstep, voffB); PG8_STAGE(PG8_SA(0, 0), a2, voffA);
;             PG8_WAIT_V(8); PG8_WAIT_L(0); PG8_BAR; PG8_MMA(1, 0, At, B0); PG8_MMA(1, 1, At, B1); PG8_BAR; PG8_SCHED;
;             PG8_LDB(B0, 1, 0); PG8_LDB(B1, 1, 1); PG8_SCHED; PG8_LDA(At, 1, 0); PG8_STAGE(PG8_SA(0, 1), a2 + hstep, voffA);
	v_mfma_f32_16x16x32_bf16 v[142:145], v[96:99], v[200:203], v[142:145]
	v_mfma_f32_16x16x32_bf16 v[142:145], v[100:103], v[204:207], v[142:145]
	v_mfma_f32_16x16x32_bf16 v[138:141], v[108:111], v[204:207], v[138:141]
	v_mfma_f32_16x16x32_bf16 v[138:141], v[104:107], v[200:203], v[138:141]
	v_mfma_f32_16x16x32_bf16 v[130:133], v[182:185], v[200:203], v[130:133]
	v_mfma_f32_16x16x32_bf16 v[130:133], v[186:189], v[204:207], v[130:133]
	v_mfma_f32_16x16x32_bf16 v[134:137], v[194:197], v[204:207], v[134:137]
	v_mfma_f32_16x16x32_bf16 v[134:137], v[190:193], v[200:203], v[134:137]
	v_mfma_f32_16x16x32_bf16 v[124:127], v[190:193], v[210:213], v[124:127]
	v_mfma_f32_16x16x32_bf16 v[124:127], v[194:197], v[226:229], v[124:127]
	v_mfma_f32_16x16x32_bf16 v[112:115], v[186:189], v[226:229], v[112:115]
	v_mfma_f32_16x16x32_bf16 v[112:115], v[182:185], v[210:213], v[112:115]
	v_mfma_f32_16x16x32_bf16 v[120:123], v[104:107], v[210:213], v[120:123]
	v_mfma_f32_16x16x32_bf16 v[120:123], v[108:111], v[226:229], v[120:123]
	v_mfma_f32_16x16x32_bf16 v[116:119], v[100:103], v[226:229], v[116:119]
	v_mfma_f32_16x16x32_bf16 v[116:119], v[96:99], v[210:213], v[116:119]
	v_mfma_f32_16x16x32_bf16 v[84:87], v[96:99], v[230:233], v[84:87]
	v_mfma_f32_16x16x32_bf16 v[84:87], v[100:103], v[234:237], v[84:87]
	v_mfma_f32_16x16x32_bf16 v[88:91], v[108:111], v[234:237], v[88:91]
	v_mfma_f32_16x16x32_bf16 v[88:91], v[104:107], v[230:233], v[88:91]
	v_mfma_f32_16x16x32_bf16 v[80:83], v[182:185], v[230:233], v[80:83]
	v_mfma_f32_16x16x32_bf16 v[80:83], v[186:189], v[234:237], v[80:83]
	v_mfma_f32_16x16x32_bf16 v[92:95], v[194:197], v[234:237], v[92:95]
	v_mfma_f32_16x16x32_bf16 v[92:95], v[190:193], v[230:233], v[92:95]
	v_mfma_f32_16x16x32_bf16 v[76:79], v[190:193], v[238:241], v[76:79]
	v_mfma_f32_16x16x32_bf16 v[76:79], v[194:197], v[242:245], v[76:79]
	v_mfma_f32_16x16x32_bf16 v[64:67], v[186:189], v[242:245], v[64:67]
	v_mfma_f32_16x16x32_bf16 v[64:67], v[182:185], v[238:241], v[64:67]
	v_mfma_f32_16x16x32_bf16 v[72:75], v[104:107], v[238:241], v[72:75]
	v_mfma_f32_16x16x32_bf16 v[72:75], v[108:111], v[242:245], v[72:75]
	v_mfma_f32_16x16x32_bf16 v[68:71], v[100:103], v[242:245], v[68:71]
	v_mfma_f32_16x16x32_bf16 v[68:71], v[96:99], v[238:241], v[68:71]
	s_barrier
	s_setprio 0
	s_add_i32 s46, s46, s38
	v_lshl_add_u64 v[162:163], s[20:21], 0, v[150:151]
	s_mov_b32 m0, s46
	ds_read_b128 v[200:203], v167 offset:16384
	ds_read_b128 v[204:207], v167 offset:17408
	ds_read_b128 v[210:213], v167 offset:18432
	ds_read_b128 v[226:229], v167 offset:19456
	ds_read_b128 v[230:233], v167 offset:20480
	ds_read_b128 v[234:237], v167 offset:21504
	ds_read_b128 v[238:241], v167 offset:22528
	ds_read_b128 v[242:245], v167 offset:23552
	global_load_lds_dwordx4 v[162:163], off
	s_add_i32 m0, s46, 0x2000
	s_add_u32 s56, s20, 0x80000
	v_lshl_add_u64 v[168:169], s[20:21], 0, v[146:147]
	s_addc_u32 s57, s21, 0
	s_add_i32 s46, s58, s38
	global_load_lds_dwordx4 v[168:169], off
	v_lshl_add_u64 v[214:215], s[56:57], 0, v[150:151]
	s_mov_b32 m0, s46
	v_lshl_add_u64 v[246:247], s[26:27], 0, v[148:149]
	global_load_lds_dwordx4 v[214:215], off
	v_lshl_add_u64 v[214:215], s[56:57], 0, v[146:147]
	s_add_i32 m0, s46, 0x2000
	s_nop 0
	global_load_lds_dwordx4 v[214:215], off
	v_lshl_add_u64 v[214:215], s[26:27], 0, v[152:153]
	s_mov_b32 m0, s43
	s_nop 0
	global_load_lds_dwordx4 v[214:215], off
	s_mov_b32 m0, s75
	s_nop 0
	global_load_lds_dwordx4 v[246:247], off
	s_waitcnt vmcnt(8)
	s_waitcnt lgkmcnt(0)
	s_setprio 1
	s_barrier
	v_mfma_f32_16x16x32_bf16 v[52:55], v[96:99], v[200:203], v[52:55]
	v_mfma_f32_16x16x32_bf16 v[52:55], v[100:103], v[204:207], v[52:55]
	v_mfma_f32_16x16x32_bf16 v[56:59], v[108:111], v[204:207], v[56:59]
	v_mfma_f32_16x16x32_bf16 v[56:59], v[104:107], v[200:203], v[56:59]
	v_mfma_f32_16x16x32_bf16 v[48:51], v[182:185], v[200:203], v[48:51]
	v_mfma_f32_16x16x32_bf16 v[48:51], v[186:189], v[204:207], v[48:51]
	v_mfma_f32_16x16x32_bf16 v[60:63], v[194:197], v[204:207], v[60:63]
	v_mfma_f32_16x16x32_bf16 v[60:63], v[190:193], v[200:203], v[60:63]
	v_mfma_f32_16x16x32_bf16 v[44:47], v[190:193], v[210:213], v[44:47]
	v_mfma_f32_16x16x32_bf16 v[44:47], v[194:197], v[226:229], v[44:47]
	v_mfma_f32_16x16x32_bf16 v[32:35], v[186:189], v[226:229], v[32:35]
	v_mfma_f32_16x16x32_bf16 v[32:35], v[182:185], v[210:213], v[32:35]
	v_mfma_f32_16x16x32_bf16 v[40:43], v[104:107], v[210:213], v[40:43]
	v_mfma_f32_16x16x32_bf16 v[40:43], v[108:111], v[226:229], v[40:43]
	v_mfma_f32_16x16x32_bf16 v[36:39], v[100:103], v[226:229], v[36:39]
	v_mfma_f32_16x16x32_bf16 v[36:39], v[96:99], v[210:213], v[36:39]
	v_mfma_f32_16x16x32_bf16 v[20:23], v[96:99], v[230:233], v[20:23]
	v_mfma_f32_16x16x32_bf16 v[20:23], v[100:103], v[234:237], v[20:23]
	v_mfma_f32_16x16x32_bf16 v[24:27], v[108:111], v[234:237], v[24:27]
	v_mfma_f32_16x16x32_bf16 v[24:27], v[104:107], v[230:233], v[24:27]
	v_mfma_f32_16x16x32_bf16 v[16:19], v[182:185], v[230:233], v[16:19]
	v_mfma_f32_16x16x32_bf16 v[16:19], v[186:189], v[234:237], v[16:19]
	v_mfma_f32_16x16x32_bf16 v[28:31], v[194:197], v[234:237], v[28:31]
	v_mfma_f32_16x16x32_bf16 v[28:31], v[190:193], v[230:233], v[28:31]
	v_mfma_f32_16x16x32_bf16 v[12:15], v[190:193], v[238:241], v[12:15]
	v_mfma_f32_16x16x32_bf16 v[12:15], v[194:197], v[242:245], v[12:15]
	v_mfma_f32_16x16x32_bf16 v[0:3], v[186:189], v[242:245], v[0:3]
	v_mfma_f32_16x16x32_bf16 v[0:3], v[182:185], v[238:241], v[0:3]
	v_mfma_f32_16x16x32_bf16 v[8:11], v[104:107], v[238:241], v[8:11]
	v_mfma_f32_16x16x32_bf16 v[8:11], v[108:111], v[242:245], v[8:11]
	v_mfma_f32_16x16x32_bf16 v[4:7], v[100:103], v[242:245], v[4:7]
	v_mfma_f32_16x16x32_bf16 v[4:7], v[96:99], v[238:241], v[4:7]
	s_barrier
; #define PG8_STAGE(bufoff, gbase, voff) do { _Pragma("unroll") for (int _i = 0; _i < 2; ++_i) \
;         __builtin_amdgcn_global_load_lds((const unsigned*)((const char*)(gbase) + (voff)[_i]), (PG8_LAS unsigned*)(lds + (bufoff) + ldsw + _i * 8192), 16, 0, 0); } while (0)
; #define PG8_LDA(dst, b, h) do { _Pragma("unroll") for (int m = 0; m < 4; ++m) _Pragma("unroll") for (int k = 0; k < 2; ++k) dst[m][k] = *(const PG8_LAS bf16x8*)(lds + PG8_SA(b, h) + aoff + m * 2048 + k * 1024); } while (0)
; #define PG8_LDB(dst, b, h) do { _Pragma("unroll") for (int n = 0; n < 2; ++n) _Pragma("unroll") for (int k = 0; k < 2; ++k) dst[n][k] = *(const PG8_LAS bf16x8*)(lds + PG8_SB(b, h) + boff + n * 2048 + k * 1024); } while (0)
; #define PG8_MMA(ai, bj, At, Bt) do { __builtin_amdgcn_s_setprio(1); _Pragma("unroll") for (int m = 0; m < 4; ++m) _Pragma("unroll") for (int n = 0; n < 2; ++n) _Pragma("unroll") for (int k = 0; k < 2; ++k) \
;         acc[ai][bj][m][n] = __builtin_amdgcn_mfma_f32_16x16x32_bf16(Bt[n][k], At[m][k], acc[ai][bj][m][n], 0, 0, 0); __builtin_amdgcn_s_setprio(0); } while (0)
; #define PG8_WAIT_V(n) asm volatile("s_waitcnt vmcnt(" #n ")" ::: "memory")
; #define PG8_WAIT_L(n) asm volatile("s_waitcnt lgkmcnt(" #n ")" ::: "memory")
; #define PG8_BAR __builtin_amdgcn_s_barrier()
; #define PG8_SCHED __builtin_amdgcn_sched_barrier(0)
; template <class Epi, class Sched, bool ALIGN_EPI = false, bool SP2 = false, class Hook = NoHook, bool REVK = false>
; __device__ __forceinline__ void gemm_phase(PG8_LAS unsigned char* lds, const Gemm g, const Sched& S, const Epi& E, const Hook H = Hook()) {
;     ...
;             PG8_LDB(B0, 1, 0); PG8_LDB(B1, 1, 1); PG8_SCHED; PG8_LDA(At, 1, 0); PG8_STAGE(PG8_SA(0, 1), a2 + hstep, voffA);
;             PG8_WAIT_V(8); PG8_WAIT_L(0); PG8_BAR; PG8_MMA(0, 0, At, B0); PG8_MMA(0, 1, At, B1); PG8_BAR; PG8_SCHED;
	s_setprio 0
	s_add_i32 s46, 0, 0x18000
	s_add_i32 s56, 0, 0x1c000
	v_add_u32_e32 v108, s46, v164
	v_add_u32_e32 v128, s56, v164
	ds_read_b128 v[96:99], v108
	ds_read_b128 v[100:103], v108 offset:1024
	ds_read_b128 v[104:107], v108 offset:2048
	ds_read_b128 v[108:111], v108 offset:3072
	ds_read_b128 v[182:185], v128
	ds_read_b128 v[186:189], v128 offset:1024
	ds_read_b128 v[190:193], v128 offset:2048
	ds_read_b128 v[194:197], v128 offset:3072
	s_add_u32 s26, s26, 0x80000
	s_addc_u32 s27, s27, 0
	s_mov_b32 m0, s77
	v_lshl_add_u64 v[248:249], s[26:27], 0, v[152:153]
	ds_read_b128 v[200:203], v167 offset:32768
	ds_read_b128 v[204:207], v167 offset:33792
	ds_read_b128 v[210:213], v167 offset:34816
	ds_read_b128 v[226:229], v167 offset:35840
	ds_read_b128 v[230:233], v167 offset:36864
	ds_read_b128 v[234:237], v167 offset:37888
	ds_read_b128 v[238:241], v167 offset:38912
	ds_read_b128 v[242:245], v167 offset:39936
	global_load_lds_dwordx4 v[248:249], off
	v_lshl_add_u64 v[248:249], s[26:27], 0, v[148:149]
	s_mov_b32 m0, s79
	s_nop 0
	global_load_lds_dwordx4 v[248:249], off
	s_waitcnt vmcnt(8)
	s_waitcnt lgkmcnt(0)
	s_setprio 1
	s_barrier
	v_mfma_f32_16x16x32_bf16 v[142:145], v[96:99], v[200:203], v[142:145]
	v_mfma_f32_16x16x32_bf16 v[142:145], v[100:103], v[204:207], v[142:145]
	v_mfma_f32_16x16x32_bf16 v[138:141], v[108:111], v[204:207], v[138:141]
	v_mfma_f32_16x16x32_bf16 v[138:141], v[104:107], v[200:203], v[138:141]
	v_mfma_f32_16x16x32_bf16 v[130:133], v[182:185], v[200:203], v[130:133]
	v_mfma_f32_16x16x32_bf16 v[130:133], v[186:189], v[204:207], v[130:133]
	v_mfma_f32_16x16x32_bf16 v[134:137], v[194:197], v[204:207], v[134:137]
	v_mfma_f32_16x16x32_bf16 v[134:137], v[190:193], v[200:203], v[134:137]
	v_mfma_f32_16x16x32_bf16 v[124:127], v[190:193], v[210:213], v[124:127]
	v_mfma_f32_16x16x32_bf16 v[124:127], v[194:197], v[226:229], v[124:127]
	v_mfma_f32_16x16x32_bf16 v[112:115], v[186:189], v[226:229], v[112:115]
	v_mfma_f32_16x16x32_bf16 v[112:115], v[182:185], v[210:213], v[112:115]
	v_mfma_f32_16x16x32_bf16 v[120:123], v[104:107], v[210:213], v[120:123]
	v_mfma_f32_16x16x32_bf16 v[120:123], v[108:111], v[226:229], v[120:123]
	v_mfma_f32_16x16x32_bf16 v[116:119], v[100:103], v[226:229], v[116:119]
	v_mfma_f32_16x16x32_bf16 v[116:119], v[96:99], v[210:213], v[116:119]
	v_mfma_f32_16x16x32_bf16 v[84:87], v[96:99], v[230:233], v[84:87]
	v_mfma_f32_16x16x32_bf16 v[84:87], v[100:103], v[234:237], v[84:87]
	v_mfma_f32_16x16x32_bf16 v[88:91], v[108:111], v[234:237], v[88:91]
	v_mfma_f32_16x16x32_bf16 v[88:91], v[104:107], v[230:233], v[88:91]
	v_mfma_f32_16x16x32_bf16 v[80:83], v[182:185], v[230:233], v[80:83]
	v_mfma_f32_16x16x32_bf16 v[80:83], v[186:189], v[234:237], v[80:83]
	v_mfma_f32_16x16x32_bf16 v[92:95], v[194:197], v[234:237], v[92:95]
	v_mfma_f32_16x16x32_bf16 v[92:95], v[190:193], v[230:233], v[92:95]
	v_mfma_f32_16x16x32_bf16 v[76:79], v[190:193], v[238:241], v[76:79]
	v_mfma_f32_16x16x32_bf16 v[76:79], v[194:197], v[242:245], v[76:79]
	v_mfma_f32_16x16x32_bf16 v[64:67], v[186:189], v[242:245], v[64:67]
	v_mfma_f32_16x16x32_bf16 v[64:67], v[182:185], v[238:241], v[64:67]
	v_mfma_f32_16x16x32_bf16 v[72:75], v[104:107], v[238:241], v[72:75]
	v_mfma_f32_16x16x32_bf16 v[72:75], v[108:111], v[242:245], v[72:75]
	v_mfma_f32_16x16x32_bf16 v[68:71], v[100:103], v[242:245], v[68:71]
	v_mfma_f32_16x16x32_bf16 v[68:71], v[96:99], v[238:241], v[68:71]
	s_barrier
; #define PG8_STAGE(bufoff, gbase, voff) do { _Pragma("unroll") for (int _i = 0; _i < 2; ++_i) \
;         __builtin_amdgcn_global_load_lds((const unsigned*)((const char*)(gbase) + (voff)[_i]), (PG8_LAS unsigned*)(lds + (bufoff) + ldsw + _i * 8192), 16, 0, 0); } while (0)
; #define PG8_LDA(dst, b, h) do { _Pragma("unroll") for (int m = 0; m < 4; ++m) _Pragma("unroll") for (int k = 0; k < 2; ++k) dst[m][k] = *(const PG8_LAS bf16x8*)(lds + PG8_SA(b, h) + aoff + m * 2048 + k * 1024); } while (0)
; #define PG8_MMA(ai, bj, At, Bt) do { __builtin_amdgcn_s_setprio(1); _Pragma("unroll") for (int m = 0; m < 4; ++m) _Pragma("unroll") for (int n = 0; n < 2; ++n) _Pragma("unroll") for (int k = 0; k < 2; ++k) \
;         acc[ai][bj][m][n] = __builtin_amdgcn_mfma_f32_16x16x32_bf16(Bt[n][k], At[m][k], acc[ai][bj][m][n], 0, 0, 0); __builtin_amdgcn_s_setprio(0); } while (0)
; #define PG8_WAIT_V(n) asm volatile("s_waitcnt vmcnt(" #n ")" ::: "memory")
; #define PG8_WAIT_L(n) asm volatile("s_waitcnt lgkmcnt(" #n ")" ::: "memory")
; #define PG8_BAR __builtin_amdgcn_s_barrier()
; #define PG8_SCHED __builtin_amdgcn_sched_barrier(0)
; template <class Epi, class Sched, bool ALIGN_EPI = false, bool SP2 = false, class Hook = NoHook, bool REVK = false>
; __device__ __forceinline__ void gemm_phase(PG8_LAS unsigned char* lds, const Gemm g, const Sched& S, const Epi& E, const Hook H = Hook()) {
;     ...
;             PG8_LDA(At, 1, 1); PG8_STAGE(PG8_SB(1, 0), b3, voffB); PG8_STAGE(PG8_SB(1, 1), b3 + hstep, voffB); PG8_STAGE(PG8_SA(1, 0), a3, voffA);
;             PG8_WAIT_V(8); PG8_WAIT_L(0); PG8_BAR; PG8_MMA(1, 0, At, B0); PG8_MMA(1, 1, At, B1); PG8_BAR; PG8_SCHED;
;     ...
;         if constexpr (ALIGN_EPI) { if (wr == 0) PG8_BAR; }
	s_setprio 0
	s_add_i32 s26, s46, s38
	v_lshl_add_u64 v[162:163], v[162:163], 0, s[64:65]
	s_mov_b32 m0, s26
	ds_read_b128 v[200:203], v167 offset:49152
	ds_read_b128 v[204:207], v167 offset:50176
	ds_read_b128 v[210:213], v167 offset:51200
	ds_read_b128 v[226:229], v167 offset:52224
	ds_read_b128 v[230:233], v167 offset:53248
	ds_read_b128 v[234:237], v167 offset:54272
	ds_read_b128 v[238:241], v167 offset:55296
	ds_read_b128 v[242:245], v167 offset:56320
	global_load_lds_dwordx4 v[162:163], off
	s_add_i32 m0, s26, 0x2000
	s_add_u32 s20, s20, 0x80080
	v_lshl_add_u64 v[162:163], v[168:169], 0, s[64:65]
	s_addc_u32 s21, s21, 0
	s_add_i32 s26, s56, s38
	global_load_lds_dwordx4 v[162:163], off
	v_lshl_add_u64 v[162:163], s[20:21], 0, v[150:151]
	s_mov_b32 m0, s26
	s_nop 0
	global_load_lds_dwordx4 v[162:163], off
	v_lshl_add_u64 v[162:163], s[20:21], 0, v[146:147]
	s_add_i32 m0, s26, 0x2000
	s_nop 0
	global_load_lds_dwordx4 v[162:163], off
	v_lshl_add_u64 v[162:163], v[214:215], 0, s[64:65]
	s_mov_b32 m0, s44
	s_nop 0
	global_load_lds_dwordx4 v[162:163], off
	v_lshl_add_u64 v[162:163], v[246:247], 0, s[64:65]
	s_mov_b32 m0, s36
	s_nop 0
	global_load_lds_dwordx4 v[162:163], off
	s_waitcnt vmcnt(8)
	s_waitcnt lgkmcnt(0)
	s_setprio 1
	s_barrier
	v_mfma_f32_16x16x32_bf16 v[52:55], v[96:99], v[200:203], v[52:55]
	v_mfma_f32_16x16x32_bf16 v[52:55], v[100:103], v[204:207], v[52:55]
	v_mfma_f32_16x16x32_bf16 v[56:59], v[108:111], v[204:207], v[56:59]
	v_mfma_f32_16x16x32_bf16 v[56:59], v[104:107], v[200:203], v[56:59]
	v_mfma_f32_16x16x32_bf16 v[48:51], v[182:185], v[200:203], v[48:51]
	v_mfma_f32_16x16x32_bf16 v[48:51], v[186:189], v[204:207], v[48:51]
	v_mfma_f32_16x16x32_bf16 v[60:63], v[194:197], v[204:207], v[60:63]
	v_mfma_f32_16x16x32_bf16 v[60:63], v[190:193], v[200:203], v[60:63]
	v_mfma_f32_16x16x32_bf16 v[44:47], v[190:193], v[210:213], v[44:47]
	v_mfma_f32_16x16x32_bf16 v[44:47], v[194:197], v[226:229], v[44:47]
	v_mfma_f32_16x16x32_bf16 v[32:35], v[186:189], v[226:229], v[32:35]
	v_mfma_f32_16x16x32_bf16 v[32:35], v[182:185], v[210:213], v[32:35]
	v_mfma_f32_16x16x32_bf16 v[40:43], v[104:107], v[210:213], v[40:43]
	v_mfma_f32_16x16x32_bf16 v[40:43], v[108:111], v[226:229], v[40:43]
	v_mfma_f32_16x16x32_bf16 v[36:39], v[100:103], v[226:229], v[36:39]
	v_mfma_f32_16x16x32_bf16 v[36:39], v[96:99], v[210:213], v[36:39]
	v_mfma_f32_16x16x32_bf16 v[20:23], v[96:99], v[230:233], v[20:23]
	v_mfma_f32_16x16x32_bf16 v[20:23], v[100:103], v[234:237], v[20:23]
	v_mfma_f32_16x16x32_bf16 v[24:27], v[108:111], v[234:237], v[24:27]
	v_mfma_f32_16x16x32_bf16 v[24:27], v[104:107], v[230:233], v[24:27]
	v_mfma_f32_16x16x32_bf16 v[16:19], v[182:185], v[230:233], v[16:19]
	v_mfma_f32_16x16x32_bf16 v[16:19], v[186:189], v[234:237], v[16:19]
	v_mfma_f32_16x16x32_bf16 v[28:31], v[194:197], v[234:237], v[28:31]
	v_mfma_f32_16x16x32_bf16 v[28:31], v[190:193], v[230:233], v[28:31]
	v_mfma_f32_16x16x32_bf16 v[12:15], v[190:193], v[238:241], v[12:15]
	v_mfma_f32_16x16x32_bf16 v[12:15], v[194:197], v[242:245], v[12:15]
	v_mfma_f32_16x16x32_bf16 v[0:3], v[186:189], v[242:245], v[0:3]
	v_mfma_f32_16x16x32_bf16 v[0:3], v[182:185], v[238:241], v[0:3]
	v_mfma_f32_16x16x32_bf16 v[8:11], v[104:107], v[238:241], v[8:11]
	v_mfma_f32_16x16x32_bf16 v[8:11], v[108:111], v[242:245], v[8:11]
	v_mfma_f32_16x16x32_bf16 v[4:7], v[100:103], v[242:245], v[4:7]
	v_mfma_f32_16x16x32_bf16 v[4:7], v[96:99], v[238:241], v[4:7]
	s_barrier
	s_setprio 0
	s_add_i32 s99, s99, 2
	s_add_u32 s22, s22, 0x100
	s_addc_u32 s23, s23, 0
	s_add_u32 s93, s93, 0x100
	s_addc_u32 s98, s98, 0
	s_cmp_gt_u32 s99, 29
	s_cbranch_scc0 .LBB0_59
	s_and_b64 vcc, exec, s[84:85]
	s_cbranch_vccz .LBB0_62
	s_barrier

; #define PG8_STAGE(bufoff, gbase, voff) do { _Pragma("unroll") for (int _i = 0; _i < 2; ++_i) \
;         __builtin_amdgcn_global_load_lds((const unsigned*)((const char*)(gbase) + (voff)[_i]), (PG8_LAS unsigned*)(lds + (bufoff) + ldsw + _i * 8192), 16, 0, 0); } while (0)
; #define PG8_LDA(dst, b, h) do { _Pragma("unroll") for (int m = 0; m < 4; ++m) _Pragma("unroll") for (int k = 0; k < 2; ++k) dst[m][k] = *(const PG8_LAS bf16x8*)(lds + PG8_SA(b, h) + aoff + m * 2048 + k * 1024); } while (0)
; #define PG8_LDB(dst, b, h) do { _Pragma("unroll") for (int n = 0; n < 2; ++n) _Pragma("unroll") for (int k = 0; k < 2; ++k) dst[n][k] = *(const PG8_LAS bf16x8*)(lds + PG8_SB(b, h) + boff + n * 2048 + k * 1024); } while (0)
; #define PG8_MMA(ai, bj, At, Bt) do { __builtin_amdgcn_s_setprio(1); _Pragma("unroll") for (int m = 0; m < 4; ++m) _Pragma("unroll") for (int n = 0; n < 2; ++n) _Pragma("unroll") for (int k = 0; k < 2; ++k) \
;         acc[ai][bj][m][n] = __builtin_amdgcn_mfma_f32_16x16x32_bf16(Bt[n][k], At[m][k], acc[ai][bj][m][n], 0, 0, 0); __builtin_amdgcn_s_setprio(0); } while (0)
; #define PG8_WAIT_V(n) asm volatile("s_waitcnt vmcnt(" #n ")" ::: "memory")
; #define PG8_WAIT_L(n) asm volatile("s_waitcnt lgkmcnt(" #n ")" ::: "memory")
; #define PG8_BAR __builtin_amdgcn_s_barrier()
; #define PG8_SCHED __builtin_amdgcn_sched_barrier(0)
; template <class Epi, class Sched, bool ALIGN_EPI = false, bool SP2 = false, class Hook = NoHook, bool REVK = false>
; __device__ __forceinline__ void gemm_phase(PG8_LAS unsigned char* lds, const Gemm g, const Sched& S, const Epi& E, const Hook H = Hook()) {
;     ...
;             const char* a2 = last ? nA : cA + (long)(t + 2) * kstep; const char* b2 = last ? nB : cB + (long)(t + 2) * kstep;
;             const char* a3 = a2 + kstep; const char* b3 = b2 + kstep;
;             if (last && has_next) S.a_ready(nxt);
;             if constexpr (SP2) {
;             PG8_LDB(B0, 0, 0); PG8_LDB(B1, 0, 1); PG8_SCHED; PG8_LDA(At, 0, 0); PG8_STAGE(PG8_SA(1, 1), a1 + hstep, voffA);
;             PG8_WAIT_V(8); PG8_WAIT_L(0); PG8_BAR; PG8_MMA(0, 0, At, B0); PG8_MMA(0, 1, At, B1); PG8_BAR; PG8_SCHED;
;             PG8_LDA(At, 0, 1); PG8_STAGE(PG8_SB(0, 0), b2, voffB); PG8_STAGE(PG8_SB(0, 1), b2 + hstep, voffB); PG8_STAGE(PG8_SA(0, 0), a2, voffA);
.LBB0_477:
	s_add_u32 s20, s22, 0xfff80080
	s_addc_u32 s21, s23, -1
	s_add_i32 s46, 0, 0x10000
	s_cmp_eq_u32 s53, 30
	s_cselect_b32 s27, s11, s21
	s_cselect_b32 s26, s42, s20
	v_add_u32_e32 v128, s46, v226
	s_cselect_b32 s21, s43, s51
	s_cselect_b32 s20, s44, s47
	s_add_i32 s58, 0, 0x14000
	ds_read_b128 v[130:133], v128
	ds_read_b128 v[134:137], v128 offset:1024
	ds_read_b128 v[138:141], v128 offset:2048
	ds_read_b128 v[142:145], v128 offset:3072
	v_add_u32_e32 v128, s58, v226
	ds_read_b128 v[146:149], v128
	ds_read_b128 v[150:153], v128 offset:1024
	ds_read_b128 v[154:157], v128 offset:2048
	ds_read_b128 v[158:161], v128 offset:3072
	v_lshl_add_u64 v[196:197], s[22:23], 0, v[182:183]
	s_add_i32 m0, s34, 0xc000
	ds_read_b128 v[186:189], v229
	ds_read_b128 v[192:195], v229 offset:1024
	ds_read_b128 v[200:203], v229 offset:2048
	ds_read_b128 v[204:207], v229 offset:3072
	ds_read_b128 v[210:213], v229 offset:4096
	ds_read_b128 v[230:233], v229 offset:5120
	ds_read_b128 v[234:237], v229 offset:6144
	ds_read_b128 v[238:241], v229 offset:7168
	global_load_lds_dwordx4 v[196:197], off
	v_lshl_add_u64 v[196:197], s[22:23], 0, v[184:185]
	s_add_i32 m0, s34, 0xe000
	s_nop 0
	global_load_lds_dwordx4 v[196:197], off
	s_waitcnt vmcnt(8)
	s_waitcnt lgkmcnt(0)
	s_setprio 1
	s_barrier
	v_mfma_f32_16x16x32_bf16 v[124:127], v[130:133], v[186:189], v[124:127]
	v_mfma_f32_16x16x32_bf16 v[124:127], v[134:137], v[192:195], v[124:127]
	v_mfma_f32_16x16x32_bf16 v[120:123], v[142:145], v[192:195], v[120:123]
	v_mfma_f32_16x16x32_bf16 v[120:123], v[138:141], v[186:189], v[120:123]
	v_mfma_f32_16x16x32_bf16 v[116:119], v[146:149], v[186:189], v[116:119]
	v_mfma_f32_16x16x32_bf16 v[116:119], v[150:153], v[192:195], v[116:119]
	v_mfma_f32_16x16x32_bf16 v[112:115], v[158:161], v[192:195], v[112:115]
	v_mfma_f32_16x16x32_bf16 v[112:115], v[154:157], v[186:189], v[112:115]
	v_mfma_f32_16x16x32_bf16 v[96:99], v[154:157], v[200:203], v[96:99]
	v_mfma_f32_16x16x32_bf16 v[96:99], v[158:161], v[204:207], v[96:99]
	v_mfma_f32_16x16x32_bf16 v[100:103], v[150:153], v[204:207], v[100:103]
	v_mfma_f32_16x16x32_bf16 v[100:103], v[146:149], v[200:203], v[100:103]
	v_mfma_f32_16x16x32_bf16 v[104:107], v[138:141], v[200:203], v[104:107]
	v_mfma_f32_16x16x32_bf16 v[104:107], v[142:145], v[204:207], v[104:107]
	v_mfma_f32_16x16x32_bf16 v[108:111], v[134:137], v[204:207], v[108:111]
	v_mfma_f32_16x16x32_bf16 v[108:111], v[130:133], v[200:203], v[108:111]
	v_mfma_f32_16x16x32_bf16 v[92:95], v[130:133], v[210:213], v[92:95]
	v_mfma_f32_16x16x32_bf16 v[92:95], v[134:137], v[230:233], v[92:95]
	v_mfma_f32_16x16x32_bf16 v[88:91], v[142:145], v[230:233], v[88:91]
	v_mfma_f32_16x16x32_bf16 v[88:91], v[138:141], v[210:213], v[88:91]
	v_mfma_f32_16x16x32_bf16 v[84:87], v[146:149], v[210:213], v[84:87]
	v_mfma_f32_16x16x32_bf16 v[84:87], v[150:153], v[230:233], v[84:87]
	v_mfma_f32_16x16x32_bf16 v[80:83], v[158:161], v[230:233], v[80:83]
	v_mfma_f32_16x16x32_bf16 v[80:83], v[154:157], v[210:213], v[80:83]
	v_mfma_f32_16x16x32_bf16 v[64:67], v[154:157], v[234:237], v[64:67]
	v_mfma_f32_16x16x32_bf16 v[64:67], v[158:161], v[238:241], v[64:67]
	v_mfma_f32_16x16x32_bf16 v[68:71], v[150:153], v[238:241], v[68:71]
	v_mfma_f32_16x16x32_bf16 v[68:71], v[146:149], v[234:237], v[68:71]
	v_mfma_f32_16x16x32_bf16 v[72:75], v[138:141], v[234:237], v[72:75]
	v_mfma_f32_16x16x32_bf16 v[72:75], v[142:145], v[238:241], v[72:75]
	v_mfma_f32_16x16x32_bf16 v[76:79], v[134:137], v[238:241], v[76:79]
	v_mfma_f32_16x16x32_bf16 v[76:79], v[130:133], v[234:237], v[76:79]
	s_barrier
	s_setprio 0
	s_add_i32 s46, s46, s24
	v_lshl_add_u64 v[196:197], s[20:21], 0, v[166:167]
	s_mov_b32 m0, s46
	ds_read_b128 v[186:189], v229 offset:16384
	ds_read_b128 v[192:195], v229 offset:17408
	ds_read_b128 v[200:203], v229 offset:18432
	ds_read_b128 v[204:207], v229 offset:19456
	ds_read_b128 v[210:213], v229 offset:20480
	ds_read_b128 v[230:233], v229 offset:21504
	ds_read_b128 v[234:237], v229 offset:22528
	ds_read_b128 v[238:241], v229 offset:23552
	global_load_lds_dwordx4 v[196:197], off
	s_add_i32 m0, s46, 0x2000
	s_add_u32 s56, s20, 0x80000
	v_lshl_add_u64 v[214:215], s[20:21], 0, v[162:163]
	s_addc_u32 s57, s21, 0
	s_add_i32 s46, s58, s24
	global_load_lds_dwordx4 v[214:215], off
	v_lshl_add_u64 v[242:243], s[56:57], 0, v[166:167]
	s_mov_b32 m0, s46
	v_lshl_add_u64 v[244:245], s[26:27], 0, v[164:165]
	global_load_lds_dwordx4 v[242:243], off
	v_lshl_add_u64 v[242:243], s[56:57], 0, v[162:163]
	s_add_i32 m0, s46, 0x2000
	s_nop 0
	global_load_lds_dwordx4 v[242:243], off
	v_lshl_add_u64 v[242:243], s[26:27], 0, v[168:169]
	s_mov_b32 m0, s34
	s_nop 0
	global_load_lds_dwordx4 v[242:243], off
	s_mov_b32 m0, s35
	s_nop 0
	global_load_lds_dwordx4 v[244:245], off
	s_waitcnt vmcnt(8)
	s_waitcnt lgkmcnt(0)
	s_setprio 1
	s_barrier
; #define PG8_STAGE(bufoff, gbase, voff) do { _Pragma("unroll") for (int _i = 0; _i < 2; ++_i) \
;         __builtin_amdgcn_global_load_lds((const unsigned*)((const char*)(gbase) + (voff)[_i]), (PG8_LAS unsigned*)(lds + (bufoff) + ldsw + _i * 8192), 16, 0, 0); } while (0)
; #define PG8_LDA(dst, b, h) do { _Pragma("unroll") for (int m = 0; m < 4; ++m) _Pragma("unroll") for (int k = 0; k < 2; ++k) dst[m][k] = *(const PG8_LAS bf16x8*)(lds + PG8_SA(b, h) + aoff + m * 2048 + k * 1024); } while (0)
; #define PG8_LDB(dst, b, h) do { _Pragma("unroll") for (int n = 0; n < 2; ++n) _Pragma("unroll") for (int k = 0; k < 2; ++k) dst[n][k] = *(const PG8_LAS bf16x8*)(lds + PG8_SB(b, h) + boff + n * 2048 + k * 1024); } while (0)
; #define PG8_MMA(ai, bj, At, Bt) do { __builtin_amdgcn_s_setprio(1); _Pragma("unroll") for (int m = 0; m < 4; ++m) _Pragma("unroll") for (int n = 0; n < 2; ++n) _Pragma("unroll") for (int k = 0; k < 2; ++k) \
;         acc[ai][bj][m][n] = __builtin_amdgcn_mfma_f32_16x16x32_bf16(Bt[n][k], At[m][k], acc[ai][bj][m][n], 0, 0, 0); __builtin_amdgcn_s_setprio(0); } while (0)
; #define PG8_WAIT_V(n) asm volatile("s_waitcnt vmcnt(" #n ")" ::: "memory")
; #define PG8_WAIT_L(n) asm volatile("s_waitcnt lgkmcnt(" #n ")" ::: "memory")
; #define PG8_BAR __builtin_amdgcn_s_barrier()
; #define PG8_SCHED __builtin_amdgcn_sched_barrier(0)
; template <class Epi, class Sched, bool ALIGN_EPI = false, bool SP2 = false, class Hook = NoHook, bool REVK = false>
; __device__ __forceinline__ void gemm_phase(PG8_LAS unsigned char* lds, const Gemm g, const Sched& S, const Epi& E, const Hook H = Hook()) {
;     ...
;             PG8_WAIT_V(8); PG8_WAIT_L(0); PG8_BAR; PG8_MMA(1, 0, At, B0); PG8_MMA(1, 1, At, B1); PG8_BAR; PG8_SCHED;
;             PG8_LDB(B0, 1, 0); PG8_LDB(B1, 1, 1); PG8_SCHED; PG8_LDA(At, 1, 0); PG8_STAGE(PG8_SA(0, 1), a2 + hstep, voffA);
;             PG8_WAIT_V(8); PG8_WAIT_L(0); PG8_BAR; PG8_MMA(0, 0, At, B0); PG8_MMA(0, 1, At, B1); PG8_BAR; PG8_SCHED;
	v_mfma_f32_16x16x32_bf16 v[60:63], v[130:133], v[186:189], v[60:63]
	v_mfma_f32_16x16x32_bf16 v[60:63], v[134:137], v[192:195], v[60:63]
	v_mfma_f32_16x16x32_bf16 v[56:59], v[142:145], v[192:195], v[56:59]
	v_mfma_f32_16x16x32_bf16 v[56:59], v[138:141], v[186:189], v[56:59]
	v_mfma_f32_16x16x32_bf16 v[52:55], v[146:149], v[186:189], v[52:55]
	v_mfma_f32_16x16x32_bf16 v[52:55], v[150:153], v[192:195], v[52:55]
	v_mfma_f32_16x16x32_bf16 v[48:51], v[158:161], v[192:195], v[48:51]
	v_mfma_f32_16x16x32_bf16 v[48:51], v[154:157], v[186:189], v[48:51]
	v_mfma_f32_16x16x32_bf16 v[32:35], v[154:157], v[200:203], v[32:35]
	v_mfma_f32_16x16x32_bf16 v[32:35], v[158:161], v[204:207], v[32:35]
	v_mfma_f32_16x16x32_bf16 v[36:39], v[150:153], v[204:207], v[36:39]
	v_mfma_f32_16x16x32_bf16 v[36:39], v[146:149], v[200:203], v[36:39]
	v_mfma_f32_16x16x32_bf16 v[40:43], v[138:141], v[200:203], v[40:43]
	v_mfma_f32_16x16x32_bf16 v[40:43], v[142:145], v[204:207], v[40:43]
	v_mfma_f32_16x16x32_bf16 v[44:47], v[134:137], v[204:207], v[44:47]
	v_mfma_f32_16x16x32_bf16 v[44:47], v[130:133], v[200:203], v[44:47]
	v_mfma_f32_16x16x32_bf16 v[28:31], v[130:133], v[210:213], v[28:31]
	v_mfma_f32_16x16x32_bf16 v[28:31], v[134:137], v[230:233], v[28:31]
	v_mfma_f32_16x16x32_bf16 v[24:27], v[142:145], v[230:233], v[24:27]
	v_mfma_f32_16x16x32_bf16 v[24:27], v[138:141], v[210:213], v[24:27]
	v_mfma_f32_16x16x32_bf16 v[20:23], v[146:149], v[210:213], v[20:23]
	v_mfma_f32_16x16x32_bf16 v[20:23], v[150:153], v[230:233], v[20:23]
	v_mfma_f32_16x16x32_bf16 v[16:19], v[158:161], v[230:233], v[16:19]
	v_mfma_f32_16x16x32_bf16 v[16:19], v[154:157], v[210:213], v[16:19]
	v_mfma_f32_16x16x32_bf16 v[0:3], v[154:157], v[234:237], v[0:3]
	v_mfma_f32_16x16x32_bf16 v[0:3], v[158:161], v[238:241], v[0:3]
	v_mfma_f32_16x16x32_bf16 v[4:7], v[150:153], v[238:241], v[4:7]
	v_mfma_f32_16x16x32_bf16 v[4:7], v[146:149], v[234:237], v[4:7]
	v_mfma_f32_16x16x32_bf16 v[8:11], v[138:141], v[234:237], v[8:11]
	v_mfma_f32_16x16x32_bf16 v[8:11], v[142:145], v[238:241], v[8:11]
	v_mfma_f32_16x16x32_bf16 v[12:15], v[134:137], v[238:241], v[12:15]
	v_mfma_f32_16x16x32_bf16 v[12:15], v[130:133], v[234:237], v[12:15]
	s_barrier
	s_setprio 0
	s_add_i32 s46, 0, 0x18000
	v_add_u32_e32 v128, s46, v226
	s_add_i32 s56, 0, 0x1c000
	ds_read_b128 v[130:133], v128
	ds_read_b128 v[134:137], v128 offset:1024
	ds_read_b128 v[138:141], v128 offset:2048
	ds_read_b128 v[142:145], v128 offset:3072
	v_add_u32_e32 v128, s56, v226
	ds_read_b128 v[146:149], v128
	ds_read_b128 v[150:153], v128 offset:1024
	ds_read_b128 v[154:157], v128 offset:2048
	ds_read_b128 v[158:161], v128 offset:3072
	s_add_u32 s26, s26, 0x80000
	s_addc_u32 s27, s27, 0
	s_mov_b32 m0, s36
	v_lshl_add_u64 v[246:247], s[26:27], 0, v[168:169]
	ds_read_b128 v[186:189], v229 offset:32768
	ds_read_b128 v[192:195], v229 offset:33792
	ds_read_b128 v[200:203], v229 offset:34816
	ds_read_b128 v[204:207], v229 offset:35840
	ds_read_b128 v[210:213], v229 offset:36864
	ds_read_b128 v[230:233], v229 offset:37888
	ds_read_b128 v[234:237], v229 offset:38912
	ds_read_b128 v[238:241], v229 offset:39936
	global_load_lds_dwordx4 v[246:247], off
	v_lshl_add_u64 v[246:247], s[26:27], 0, v[164:165]
	s_mov_b32 m0, s38
	s_nop 0
	global_load_lds_dwordx4 v[246:247], off
	s_waitcnt vmcnt(8)
	s_waitcnt lgkmcnt(0)
	s_setprio 1
	s_barrier
	v_mfma_f32_16x16x32_bf16 v[124:127], v[130:133], v[186:189], v[124:127]
	v_mfma_f32_16x16x32_bf16 v[124:127], v[134:137], v[192:195], v[124:127]
	v_mfma_f32_16x16x32_bf16 v[120:123], v[142:145], v[192:195], v[120:123]
	v_mfma_f32_16x16x32_bf16 v[120:123], v[138:141], v[186:189], v[120:123]
	v_mfma_f32_16x16x32_bf16 v[116:119], v[146:149], v[186:189], v[116:119]
	v_mfma_f32_16x16x32_bf16 v[116:119], v[150:153], v[192:195], v[116:119]
	v_mfma_f32_16x16x32_bf16 v[112:115], v[158:161], v[192:195], v[112:115]
	v_mfma_f32_16x16x32_bf16 v[112:115], v[154:157], v[186:189], v[112:115]
	v_mfma_f32_16x16x32_bf16 v[96:99], v[154:157], v[200:203], v[96:99]
	v_mfma_f32_16x16x32_bf16 v[96:99], v[158:161], v[204:207], v[96:99]
	v_mfma_f32_16x16x32_bf16 v[100:103], v[150:153], v[204:207], v[100:103]
	v_mfma_f32_16x16x32_bf16 v[100:103], v[146:149], v[200:203], v[100:103]
	v_mfma_f32_16x16x32_bf16 v[104:107], v[138:141], v[200:203], v[104:107]
	v_mfma_f32_16x16x32_bf16 v[104:107], v[142:145], v[204:207], v[104:107]
	v_mfma_f32_16x16x32_bf16 v[108:111], v[134:137], v[204:207], v[108:111]
	v_mfma_f32_16x16x32_bf16 v[108:111], v[130:133], v[200:203], v[108:111]
	v_mfma_f32_16x16x32_bf16 v[92:95], v[130:133], v[210:213], v[92:95]
	v_mfma_f32_16x16x32_bf16 v[92:95], v[134:137], v[230:233], v[92:95]
	v_mfma_f32_16x16x32_bf16 v[88:91], v[142:145], v[230:233], v[88:91]
	v_mfma_f32_16x16x32_bf16 v[88:91], v[138:141], v[210:213], v[88:91]
	v_mfma_f32_16x16x32_bf16 v[84:87], v[146:149], v[210:213], v[84:87]
	v_mfma_f32_16x16x32_bf16 v[84:87], v[150:153], v[230:233], v[84:87]
	v_mfma_f32_16x16x32_bf16 v[80:83], v[158:161], v[230:233], v[80:83]
	v_mfma_f32_16x16x32_bf16 v[80:83], v[154:157], v[210:213], v[80:83]
	v_mfma_f32_16x16x32_bf16 v[64:67], v[154:157], v[234:237], v[64:67]
	v_mfma_f32_16x16x32_bf16 v[64:67], v[158:161], v[238:241], v[64:67]
	v_mfma_f32_16x16x32_bf16 v[68:71], v[150:153], v[238:241], v[68:71]
	v_mfma_f32_16x16x32_bf16 v[68:71], v[146:149], v[234:237], v[68:71]
	v_mfma_f32_16x16x32_bf16 v[72:75], v[138:141], v[234:237], v[72:75]
	v_mfma_f32_16x16x32_bf16 v[72:75], v[142:145], v[238:241], v[72:75]
	v_mfma_f32_16x16x32_bf16 v[76:79], v[134:137], v[238:241], v[76:79]
	v_mfma_f32_16x16x32_bf16 v[76:79], v[130:133], v[234:237], v[76:79]
	s_barrier
; #define PG8_STAGE(bufoff, gbase, voff) do { _Pragma("unroll") for (int _i = 0; _i < 2; ++_i) \
;         __builtin_amdgcn_global_load_lds((const unsigned*)((const char*)(gbase) + (voff)[_i]), (PG8_LAS unsigned*)(lds + (bufoff) + ldsw + _i * 8192), 16, 0, 0); } while (0)
; #define PG8_LDA(dst, b, h) do { _Pragma("unroll") for (int m = 0; m < 4; ++m) _Pragma("unroll") for (int k = 0; k < 2; ++k) dst[m][k] = *(const PG8_LAS bf16x8*)(lds + PG8_SA(b, h) + aoff + m * 2048 + k * 1024); } while (0)
; #define PG8_MMA(ai, bj, At, Bt) do { __builtin_amdgcn_s_setprio(1); _Pragma("unroll") for (int m = 0; m < 4; ++m) _Pragma("unroll") for (int n = 0; n < 2; ++n) _Pragma("unroll") for (int k = 0; k < 2; ++k) \
;         acc[ai][bj][m][n] = __builtin_amdgcn_mfma_f32_16x16x32_bf16(Bt[n][k], At[m][k], acc[ai][bj][m][n], 0, 0, 0); __builtin_amdgcn_s_setprio(0); } while (0)
; #define PG8_WAIT_V(n) asm volatile("s_waitcnt vmcnt(" #n ")" ::: "memory")
; #define PG8_WAIT_L(n) asm volatile("s_waitcnt lgkmcnt(" #n ")" ::: "memory")
; #define PG8_BAR __builtin_amdgcn_s_barrier()
; #define PG8_SCHED __builtin_amdgcn_sched_barrier(0)
; template <class Epi, class Sched, bool ALIGN_EPI = false, bool SP2 = false, class Hook = NoHook, bool REVK = false>
; __device__ __forceinline__ void gemm_phase(PG8_LAS unsigned char* lds, const Gemm g, const Sched& S, const Epi& E, const Hook H = Hook()) {
;     ...
;             if constexpr (Hook::ENABLED) H(acc, t, nt, ui, wr, fr);
;     ...
;             PG8_LDA(At, 1, 1); PG8_STAGE(PG8_SB(1, 0), b3, voffB); PG8_STAGE(PG8_SB(1, 1), b3 + hstep, voffB); PG8_STAGE(PG8_SA(1, 0), a3, voffA);
;             PG8_WAIT_V(8); PG8_WAIT_L(0); PG8_BAR; PG8_MMA(1, 0, At, B0); PG8_MMA(1, 1, At, B1); PG8_BAR; PG8_SCHED;
	s_setprio 0
	s_add_i32 s26, s46, s24
	v_lshl_add_u64 v[196:197], v[196:197], 0, s[64:65]
	s_mov_b32 m0, s26
	ds_read_b128 v[186:189], v229 offset:49152
	ds_read_b128 v[192:195], v229 offset:50176
	ds_read_b128 v[200:203], v229 offset:51200
	ds_read_b128 v[204:207], v229 offset:52224
	ds_read_b128 v[210:213], v229 offset:53248
	ds_read_b128 v[230:233], v229 offset:54272
	ds_read_b128 v[234:237], v229 offset:55296
	ds_read_b128 v[238:241], v229 offset:56320
	global_load_lds_dwordx4 v[196:197], off
	s_add_i32 m0, s26, 0x2000
	s_add_u32 s20, s20, 0x80080
	v_lshl_add_u64 v[196:197], v[214:215], 0, s[64:65]
	s_addc_u32 s21, s21, 0
	s_add_i32 s26, s56, s24
	global_load_lds_dwordx4 v[196:197], off
	v_lshl_add_u64 v[196:197], s[20:21], 0, v[166:167]
	s_mov_b32 m0, s26
	s_nop 0
	global_load_lds_dwordx4 v[196:197], off
	v_lshl_add_u64 v[196:197], s[20:21], 0, v[162:163]
	s_add_i32 m0, s26, 0x2000
	s_nop 0
	global_load_lds_dwordx4 v[196:197], off
	v_lshl_add_u64 v[196:197], v[242:243], 0, s[64:65]
	s_mov_b32 m0, s39
	s_nop 0
	global_load_lds_dwordx4 v[196:197], off
	v_lshl_add_u64 v[196:197], v[244:245], 0, s[64:65]
	s_mov_b32 m0, s40
	s_nop 0
	global_load_lds_dwordx4 v[196:197], off
	s_waitcnt vmcnt(8)
	s_waitcnt lgkmcnt(0)
	s_setprio 1
	s_barrier
	v_mfma_f32_16x16x32_bf16 v[60:63], v[130:133], v[186:189], v[60:63]
	v_mfma_f32_16x16x32_bf16 v[60:63], v[134:137], v[192:195], v[60:63]
	v_mfma_f32_16x16x32_bf16 v[56:59], v[142:145], v[192:195], v[56:59]
	v_mfma_f32_16x16x32_bf16 v[56:59], v[138:141], v[186:189], v[56:59]
	v_mfma_f32_16x16x32_bf16 v[52:55], v[146:149], v[186:189], v[52:55]
	v_mfma_f32_16x16x32_bf16 v[52:55], v[150:153], v[192:195], v[52:55]
	v_mfma_f32_16x16x32_bf16 v[48:51], v[158:161], v[192:195], v[48:51]
	v_mfma_f32_16x16x32_bf16 v[48:51], v[154:157], v[186:189], v[48:51]
	v_mfma_f32_16x16x32_bf16 v[32:35], v[154:157], v[200:203], v[32:35]
	v_mfma_f32_16x16x32_bf16 v[32:35], v[158:161], v[204:207], v[32:35]
	v_mfma_f32_16x16x32_bf16 v[36:39], v[150:153], v[204:207], v[36:39]
	v_mfma_f32_16x16x32_bf16 v[36:39], v[146:149], v[200:203], v[36:39]
	v_mfma_f32_16x16x32_bf16 v[40:43], v[138:141], v[200:203], v[40:43]
	v_mfma_f32_16x16x32_bf16 v[40:43], v[142:145], v[204:207], v[40:43]
	v_mfma_f32_16x16x32_bf16 v[44:47], v[134:137], v[204:207], v[44:47]
	v_mfma_f32_16x16x32_bf16 v[44:47], v[130:133], v[200:203], v[44:47]
	v_mfma_f32_16x16x32_bf16 v[28:31], v[130:133], v[210:213], v[28:31]
	v_mfma_f32_16x16x32_bf16 v[28:31], v[134:137], v[230:233], v[28:31]
	v_mfma_f32_16x16x32_bf16 v[24:27], v[142:145], v[230:233], v[24:27]
	v_mfma_f32_16x16x32_bf16 v[24:27], v[138:141], v[210:213], v[24:27]
	v_mfma_f32_16x16x32_bf16 v[20:23], v[146:149], v[210:213], v[20:23]
	v_mfma_f32_16x16x32_bf16 v[20:23], v[150:153], v[230:233], v[20:23]
	v_mfma_f32_16x16x32_bf16 v[16:19], v[158:161], v[230:233], v[16:19]
	v_mfma_f32_16x16x32_bf16 v[16:19], v[154:157], v[210:213], v[16:19]
	v_mfma_f32_16x16x32_bf16 v[0:3], v[154:157], v[234:237], v[0:3]
	v_mfma_f32_16x16x32_bf16 v[0:3], v[158:161], v[238:241], v[0:3]
	v_mfma_f32_16x16x32_bf16 v[4:7], v[150:153], v[238:241], v[4:7]
	v_mfma_f32_16x16x32_bf16 v[4:7], v[146:149], v[234:237], v[4:7]
	v_mfma_f32_16x16x32_bf16 v[8:11], v[138:141], v[234:237], v[8:11]
	v_mfma_f32_16x16x32_bf16 v[8:11], v[142:145], v[238:241], v[8:11]
	v_mfma_f32_16x16x32_bf16 v[12:15], v[134:137], v[238:241], v[12:15]
	v_mfma_f32_16x16x32_bf16 v[12:15], v[130:133], v[234:237], v[12:15]
	s_barrier
	s_setprio 0
	s_add_i32 s20, s53, 2
	s_add_u32 s22, s22, 0x100
	s_addc_u32 s23, s23, 0
	s_add_u32 s47, s47, 0x100
	s_addc_u32 s51, s51, 0
	s_cmp_gt_u32 s53, 29
	s_cbranch_scc1 .LBB0_482
	s_mov_b32 s53, s20
	s_cmp_lt_i32 s53, 16
	s_cbranch_scc0 .LBB0_473

; #define PG8_STAGE(bufoff, gbase, voff) do { _Pragma("unroll") for (int _i = 0; _i < 2; ++_i) \
;         __builtin_amdgcn_global_load_lds((const unsigned*)((const char*)(gbase) + (voff)[_i]), (PG8_LAS unsigned*)(lds + (bufoff) + ldsw + _i * 8192), 16, 0, 0); } while (0)
; #define PG8_LDA(dst, b, h) do { _Pragma("unroll") for (int m = 0; m < 4; ++m) _Pragma("unroll") for (int k = 0; k < 2; ++k) dst[m][k] = *(const PG8_LAS bf16x8*)(lds + PG8_SA(b, h) + aoff + m * 2048 + k * 1024); } while (0)
; #define PG8_LDB(dst, b, h) do { _Pragma("unroll") for (int n = 0; n < 2; ++n) _Pragma("unroll") for (int k = 0; k < 2; ++k) dst[n][k] = *(const PG8_LAS bf16x8*)(lds + PG8_SB(b, h) + boff + n * 2048 + k * 1024); } while (0)
; #define PG8_WAIT_V(n) asm volatile("s_waitcnt vmcnt(" #n ")" ::: "memory")
; #define PG8_WAIT_L(n) asm volatile("s_waitcnt lgkmcnt(" #n ")" ::: "memory")
; template <class Epi, class Sched, bool ALIGN_EPI = false, bool SP2 = false, class Hook = NoHook, bool REVK = false>
; __device__ __forceinline__ void gemm_phase(PG8_LAS unsigned char* lds, const Gemm g, const Sched& S, const Epi& E, const Hook H = Hook()) {
;     ...
;         const bool has_next = S.next(ui + 1, nxt);
;         const char* nA = has_next ? (const char*)g.A + (size_t)nxt.pm * tstep + krev : cA; const char* nB = has_next ? (const char*)g.Bt + (size_t)nxt.pn * tstep + krev : cB;
;         for (int t = 0; t < nt; t += 2) {
;             if constexpr (Hook::ENABLED) H(acc, t, nt, ui, wr, fr);
;             const bool last = (t == nt - 2);
;             const char* a1 = cA + (long)(t + 1) * kstep;
;             const char* a2 = last ? nA : cA + (long)(t + 2) * kstep; const char* b2 = last ? nB : cB + (long)(t + 2) * kstep;
;             const char* a3 = a2 + kstep; const char* b3 = b2 + kstep;
;             if (last && has_next) S.a_ready(nxt);
;             if constexpr (SP2) {
;             PG8_LDB(B0, 0, 0); PG8_LDB(B1, 0, 1); PG8_SCHED; PG8_LDA(At, 0, 0); PG8_STAGE(PG8_SA(1, 1), a1 + hstep, voffA);
;             PG8_WAIT_V(8); PG8_WAIT_L(0); PG8_BAR; PG8_MMA(0, 0, At, B0); PG8_MMA(0, 1, At, B1); PG8_BAR; PG8_SCHED;
;             PG8_LDA(At, 0, 1); PG8_STAGE(PG8_SB(0, 0), b2, voffB); PG8_STAGE(PG8_SB(0, 1), b2 + hstep, voffB); PG8_STAGE(PG8_SA(0, 0), a2, voffA);
;             PG8_WAIT_V(8); PG8_WAIT_L(0); PG8_BAR; PG8_MMA(1, 0, At, B0); PG8_MMA(1, 1, At, B1); PG8_BAR; PG8_SCHED;
.LBB0_581:
	s_ashr_i32 s87, s86, 31
	s_lshl_b64 s[26:27], s[86:87], 20
	s_add_u32 s88, s11, s26
	s_addc_u32 s89, s24, s27
	s_and_b64 s[26:27], s[6:7], exec
	s_cselect_b32 s41, s89, s23
	s_cselect_b32 s42, s88, s22
	s_ashr_i32 s85, s84, 31
	s_lshl_b64 s[26:27], s[84:85], 20
	s_add_u32 s90, s28, s26
	s_addc_u32 s91, s29, s27
	s_and_b64 s[26:27], s[6:7], exec
	s_cselect_b32 s43, s91, s21
	s_cselect_b32 s44, s90, s20
	s_add_u32 s22, s22, 0x80080
	s_addc_u32 s23, s23, 0
	s_add_u32 s47, s20, 0x100
	s_addc_u32 s51, s21, 0
	s_mov_b32 s53, -2
	s_add_u32 s20, s22, 0xfff80080
	s_addc_u32 s21, s23, -1
	s_add_i32 s46, 0, 0x10000
	s_cmp_eq_u32 s53, 28
	s_cselect_b32 s27, s41, s21
	s_cselect_b32 s26, s42, s20
	v_add_u32_e32 v144, s46, v147
	s_cselect_b32 s21, s43, s51
	s_cselect_b32 s20, s44, s47
	s_add_i32 s58, 0, 0x14000
	ds_read_b128 v[140:143], v144
	ds_read_b128 v[152:155], v144 offset:1024
	ds_read_b128 v[156:159], v144 offset:2048
	ds_read_b128 v[160:163], v144 offset:3072
	v_add_u32_e32 v144, s58, v147
	ds_read_b128 v[164:167], v144
	ds_read_b128 v[182:185], v144 offset:1024
	ds_read_b128 v[186:189], v144 offset:2048
	ds_read_b128 v[190:193], v144 offset:3072
	v_lshl_add_u64 v[144:145], s[22:23], 0, v[136:137]
	s_add_i32 m0, s30, 0xc000
	ds_read_b128 v[194:197], v150
	ds_read_b128 v[200:203], v150 offset:1024
	ds_read_b128 v[204:207], v150 offset:2048
	ds_read_b128 v[210:213], v150 offset:3072
	ds_read_b128 v[226:229], v150 offset:4096
	ds_read_b128 v[230:233], v150 offset:5120
	ds_read_b128 v[234:237], v150 offset:6144
	ds_read_b128 v[238:241], v150 offset:7168
	global_load_lds_dwordx4 v[144:145], off
	v_lshl_add_u64 v[144:145], s[22:23], 0, v[138:139]
	s_add_i32 m0, s30, 0xe000
	s_nop 0
	global_load_lds_dwordx4 v[144:145], off
	s_waitcnt vmcnt(8)
	s_waitcnt lgkmcnt(0)
	s_setprio 1
	s_barrier
	v_mfma_f32_16x16x32_bf16 v[124:127], v[140:143], v[194:197], 0
	v_mfma_f32_16x16x32_bf16 v[124:127], v[152:155], v[200:203], v[124:127]
	v_mfma_f32_16x16x32_bf16 v[120:123], v[160:163], v[200:203], 0
	v_mfma_f32_16x16x32_bf16 v[120:123], v[156:159], v[194:197], v[120:123]
	v_mfma_f32_16x16x32_bf16 v[116:119], v[164:167], v[194:197], 0
	v_mfma_f32_16x16x32_bf16 v[116:119], v[182:185], v[200:203], v[116:119]
	v_mfma_f32_16x16x32_bf16 v[112:115], v[190:193], v[200:203], 0
	v_mfma_f32_16x16x32_bf16 v[112:115], v[186:189], v[194:197], v[112:115]
	v_mfma_f32_16x16x32_bf16 v[96:99], v[186:189], v[204:207], 0
	v_mfma_f32_16x16x32_bf16 v[96:99], v[190:193], v[210:213], v[96:99]
	v_mfma_f32_16x16x32_bf16 v[100:103], v[182:185], v[210:213], 0
	v_mfma_f32_16x16x32_bf16 v[100:103], v[164:167], v[204:207], v[100:103]
	v_mfma_f32_16x16x32_bf16 v[104:107], v[156:159], v[204:207], 0
	v_mfma_f32_16x16x32_bf16 v[104:107], v[160:163], v[210:213], v[104:107]
	v_mfma_f32_16x16x32_bf16 v[108:111], v[152:155], v[210:213], 0
	v_mfma_f32_16x16x32_bf16 v[108:111], v[140:143], v[204:207], v[108:111]
	v_mfma_f32_16x16x32_bf16 v[92:95], v[140:143], v[226:229], 0
	v_mfma_f32_16x16x32_bf16 v[92:95], v[152:155], v[230:233], v[92:95]
	v_mfma_f32_16x16x32_bf16 v[88:91], v[160:163], v[230:233], 0
	v_mfma_f32_16x16x32_bf16 v[88:91], v[156:159], v[226:229], v[88:91]
	v_mfma_f32_16x16x32_bf16 v[84:87], v[164:167], v[226:229], 0
	v_mfma_f32_16x16x32_bf16 v[84:87], v[182:185], v[230:233], v[84:87]
	v_mfma_f32_16x16x32_bf16 v[80:83], v[190:193], v[230:233], 0
	v_mfma_f32_16x16x32_bf16 v[80:83], v[186:189], v[226:229], v[80:83]
	v_mfma_f32_16x16x32_bf16 v[64:67], v[186:189], v[234:237], 0
	v_mfma_f32_16x16x32_bf16 v[64:67], v[190:193], v[238:241], v[64:67]
	v_mfma_f32_16x16x32_bf16 v[68:71], v[182:185], v[238:241], 0
	v_mfma_f32_16x16x32_bf16 v[68:71], v[164:167], v[234:237], v[68:71]
	v_mfma_f32_16x16x32_bf16 v[72:75], v[156:159], v[234:237], 0
	v_mfma_f32_16x16x32_bf16 v[72:75], v[160:163], v[238:241], v[72:75]
	v_mfma_f32_16x16x32_bf16 v[76:79], v[152:155], v[238:241], 0
	v_mfma_f32_16x16x32_bf16 v[76:79], v[140:143], v[234:237], v[76:79]
	s_barrier
	s_setprio 0
	s_add_i32 s46, s46, s10
	v_lshl_add_u64 v[144:145], s[20:21], 0, v[128:129]
	s_mov_b32 m0, s46
	ds_read_b128 v[194:197], v150 offset:16384
	ds_read_b128 v[200:203], v150 offset:17408
	ds_read_b128 v[204:207], v150 offset:18432
	ds_read_b128 v[210:213], v150 offset:19456
	ds_read_b128 v[226:229], v150 offset:20480
	ds_read_b128 v[230:233], v150 offset:21504
	ds_read_b128 v[234:237], v150 offset:22528
	ds_read_b128 v[238:241], v150 offset:23552
	global_load_lds_dwordx4 v[144:145], off
	s_add_i32 m0, s46, 0x2000
	s_add_u32 s56, s20, 0x80000
	v_lshl_add_u64 v[168:169], s[20:21], 0, v[130:131]
	s_addc_u32 s57, s21, 0
	s_add_i32 s46, s58, s10
	global_load_lds_dwordx4 v[168:169], off
	v_lshl_add_u64 v[214:215], s[56:57], 0, v[128:129]
	s_mov_b32 m0, s46
	v_lshl_add_u64 v[242:243], s[26:27], 0, v[132:133]
	global_load_lds_dwordx4 v[214:215], off
	v_lshl_add_u64 v[214:215], s[56:57], 0, v[130:131]
	s_add_i32 m0, s46, 0x2000
	s_nop 0
	global_load_lds_dwordx4 v[214:215], off
	v_lshl_add_u64 v[214:215], s[26:27], 0, v[134:135]
	s_mov_b32 m0, s30
	s_nop 0
	global_load_lds_dwordx4 v[214:215], off
	s_mov_b32 m0, s31
	s_nop 0
	global_load_lds_dwordx4 v[242:243], off
	s_waitcnt vmcnt(8)
	s_waitcnt lgkmcnt(0)
	s_setprio 1
	s_barrier
; #define PG8_STAGE(bufoff, gbase, voff) do { _Pragma("unroll") for (int _i = 0; _i < 2; ++_i) \
;         __builtin_amdgcn_global_load_lds((const unsigned*)((const char*)(gbase) + (voff)[_i]), (PG8_LAS unsigned*)(lds + (bufoff) + ldsw + _i * 8192), 16, 0, 0); } while (0)
; #define PG8_LDA(dst, b, h) do { _Pragma("unroll") for (int m = 0; m < 4; ++m) _Pragma("unroll") for (int k = 0; k < 2; ++k) dst[m][k] = *(const PG8_LAS bf16x8*)(lds + PG8_SA(b, h) + aoff + m * 2048 + k * 1024); } while (0)
; #define PG8_LDB(dst, b, h) do { _Pragma("unroll") for (int n = 0; n < 2; ++n) _Pragma("unroll") for (int k = 0; k < 2; ++k) dst[n][k] = *(const PG8_LAS bf16x8*)(lds + PG8_SB(b, h) + boff + n * 2048 + k * 1024); } while (0)
; #define PG8_MMA(ai, bj, At, Bt) do { __builtin_amdgcn_s_setprio(1); _Pragma("unroll") for (int m = 0; m < 4; ++m) _Pragma("unroll") for (int n = 0; n < 2; ++n) _Pragma("unroll") for (int k = 0; k < 2; ++k) \
;         acc[ai][bj][m][n] = __builtin_amdgcn_mfma_f32_16x16x32_bf16(Bt[n][k], At[m][k], acc[ai][bj][m][n], 0, 0, 0); __builtin_amdgcn_s_setprio(0); } while (0)
; #define PG8_WAIT_V(n) asm volatile("s_waitcnt vmcnt(" #n ")" ::: "memory")
; #define PG8_WAIT_L(n) asm volatile("s_waitcnt lgkmcnt(" #n ")" ::: "memory")
; #define PG8_BAR __builtin_amdgcn_s_barrier()
; #define PG8_SCHED __builtin_amdgcn_sched_barrier(0)
; template <class Epi, class Sched, bool ALIGN_EPI = false, bool SP2 = false, class Hook = NoHook, bool REVK = false>
; __device__ __forceinline__ void gemm_phase(PG8_LAS unsigned char* lds, const Gemm g, const Sched& S, const Epi& E, const Hook H = Hook()) {
;     ...
;             PG8_WAIT_V(8); PG8_WAIT_L(0); PG8_BAR; PG8_MMA(1, 0, At, B0); PG8_MMA(1, 1, At, B1); PG8_BAR; PG8_SCHED;
;             PG8_LDB(B0, 1, 0); PG8_LDB(B1, 1, 1); PG8_SCHED; PG8_LDA(At, 1, 0); PG8_STAGE(PG8_SA(0, 1), a2 + hstep, voffA);
;             PG8_WAIT_V(8); PG8_WAIT_L(0); PG8_BAR; PG8_MMA(0, 0, At, B0); PG8_MMA(0, 1, At, B1); PG8_BAR; PG8_SCHED;
	v_mfma_f32_16x16x32_bf16 v[60:63], v[140:143], v[194:197], 0
	v_mfma_f32_16x16x32_bf16 v[60:63], v[152:155], v[200:203], v[60:63]
	v_mfma_f32_16x16x32_bf16 v[56:59], v[160:163], v[200:203], 0
	v_mfma_f32_16x16x32_bf16 v[56:59], v[156:159], v[194:197], v[56:59]
	v_mfma_f32_16x16x32_bf16 v[52:55], v[164:167], v[194:197], 0
	v_mfma_f32_16x16x32_bf16 v[52:55], v[182:185], v[200:203], v[52:55]
	v_mfma_f32_16x16x32_bf16 v[48:51], v[190:193], v[200:203], 0
	v_mfma_f32_16x16x32_bf16 v[48:51], v[186:189], v[194:197], v[48:51]
	v_mfma_f32_16x16x32_bf16 v[32:35], v[186:189], v[204:207], 0
	v_mfma_f32_16x16x32_bf16 v[32:35], v[190:193], v[210:213], v[32:35]
	v_mfma_f32_16x16x32_bf16 v[36:39], v[182:185], v[210:213], 0
	v_mfma_f32_16x16x32_bf16 v[36:39], v[164:167], v[204:207], v[36:39]
	v_mfma_f32_16x16x32_bf16 v[40:43], v[156:159], v[204:207], 0
	v_mfma_f32_16x16x32_bf16 v[40:43], v[160:163], v[210:213], v[40:43]
	v_mfma_f32_16x16x32_bf16 v[44:47], v[152:155], v[210:213], 0
	v_mfma_f32_16x16x32_bf16 v[44:47], v[140:143], v[204:207], v[44:47]
	v_mfma_f32_16x16x32_bf16 v[28:31], v[140:143], v[226:229], 0
	v_mfma_f32_16x16x32_bf16 v[28:31], v[152:155], v[230:233], v[28:31]
	v_mfma_f32_16x16x32_bf16 v[24:27], v[160:163], v[230:233], 0
	v_mfma_f32_16x16x32_bf16 v[24:27], v[156:159], v[226:229], v[24:27]
	v_mfma_f32_16x16x32_bf16 v[20:23], v[164:167], v[226:229], 0
	v_mfma_f32_16x16x32_bf16 v[20:23], v[182:185], v[230:233], v[20:23]
	v_mfma_f32_16x16x32_bf16 v[16:19], v[190:193], v[230:233], 0
	v_mfma_f32_16x16x32_bf16 v[16:19], v[186:189], v[226:229], v[16:19]
	v_mfma_f32_16x16x32_bf16 v[0:3], v[186:189], v[234:237], 0
	v_mfma_f32_16x16x32_bf16 v[0:3], v[190:193], v[238:241], v[0:3]
	v_mfma_f32_16x16x32_bf16 v[4:7], v[182:185], v[238:241], 0
	v_mfma_f32_16x16x32_bf16 v[4:7], v[164:167], v[234:237], v[4:7]
	v_mfma_f32_16x16x32_bf16 v[8:11], v[156:159], v[234:237], 0
	v_mfma_f32_16x16x32_bf16 v[8:11], v[160:163], v[238:241], v[8:11]
	v_mfma_f32_16x16x32_bf16 v[12:15], v[152:155], v[238:241], 0
	v_mfma_f32_16x16x32_bf16 v[12:15], v[140:143], v[234:237], v[12:15]
	s_barrier
	s_setprio 0
	s_add_i32 s46, 0, 0x18000
	v_add_u32_e32 v151, s46, v147
	s_add_i32 s56, 0, 0x1c000
	ds_read_b128 v[140:143], v151
	ds_read_b128 v[152:155], v151 offset:1024
	ds_read_b128 v[156:159], v151 offset:2048
	ds_read_b128 v[160:163], v151 offset:3072
	v_add_u32_e32 v151, s56, v147
	ds_read_b128 v[164:167], v151
	ds_read_b128 v[182:185], v151 offset:1024
	ds_read_b128 v[186:189], v151 offset:2048
	ds_read_b128 v[190:193], v151 offset:3072
	s_add_u32 s26, s26, 0x80000
	s_addc_u32 s27, s27, 0
	s_mov_b32 m0, s34
	v_lshl_add_u64 v[244:245], s[26:27], 0, v[134:135]
	ds_read_b128 v[194:197], v150 offset:32768
	ds_read_b128 v[200:203], v150 offset:33792
	ds_read_b128 v[204:207], v150 offset:34816
	ds_read_b128 v[210:213], v150 offset:35840
	ds_read_b128 v[226:229], v150 offset:36864
	ds_read_b128 v[230:233], v150 offset:37888
	ds_read_b128 v[234:237], v150 offset:38912
	ds_read_b128 v[238:241], v150 offset:39936
	global_load_lds_dwordx4 v[244:245], off
	v_lshl_add_u64 v[244:245], s[26:27], 0, v[132:133]
	s_mov_b32 m0, s35
	s_nop 0
	global_load_lds_dwordx4 v[244:245], off
	s_waitcnt vmcnt(8)
	s_waitcnt lgkmcnt(0)
	s_setprio 1
	s_barrier
	v_mfma_f32_16x16x32_bf16 v[124:127], v[140:143], v[194:197], v[124:127]
	v_mfma_f32_16x16x32_bf16 v[124:127], v[152:155], v[200:203], v[124:127]
	v_mfma_f32_16x16x32_bf16 v[120:123], v[160:163], v[200:203], v[120:123]
	v_mfma_f32_16x16x32_bf16 v[120:123], v[156:159], v[194:197], v[120:123]
	v_mfma_f32_16x16x32_bf16 v[116:119], v[164:167], v[194:197], v[116:119]
	v_mfma_f32_16x16x32_bf16 v[116:119], v[182:185], v[200:203], v[116:119]
	v_mfma_f32_16x16x32_bf16 v[112:115], v[190:193], v[200:203], v[112:115]
	v_mfma_f32_16x16x32_bf16 v[112:115], v[186:189], v[194:197], v[112:115]
	v_mfma_f32_16x16x32_bf16 v[96:99], v[186:189], v[204:207], v[96:99]
	v_mfma_f32_16x16x32_bf16 v[96:99], v[190:193], v[210:213], v[96:99]
	v_mfma_f32_16x16x32_bf16 v[100:103], v[182:185], v[210:213], v[100:103]
	v_mfma_f32_16x16x32_bf16 v[100:103], v[164:167], v[204:207], v[100:103]
	v_mfma_f32_16x16x32_bf16 v[104:107], v[156:159], v[204:207], v[104:107]
	v_mfma_f32_16x16x32_bf16 v[104:107], v[160:163], v[210:213], v[104:107]
	v_mfma_f32_16x16x32_bf16 v[108:111], v[152:155], v[210:213], v[108:111]
	v_mfma_f32_16x16x32_bf16 v[108:111], v[140:143], v[204:207], v[108:111]
	v_mfma_f32_16x16x32_bf16 v[92:95], v[140:143], v[226:229], v[92:95]
	v_mfma_f32_16x16x32_bf16 v[92:95], v[152:155], v[230:233], v[92:95]
	v_mfma_f32_16x16x32_bf16 v[88:91], v[160:163], v[230:233], v[88:91]
	v_mfma_f32_16x16x32_bf16 v[88:91], v[156:159], v[226:229], v[88:91]
	v_mfma_f32_16x16x32_bf16 v[84:87], v[164:167], v[226:229], v[84:87]
	v_mfma_f32_16x16x32_bf16 v[84:87], v[182:185], v[230:233], v[84:87]
	v_mfma_f32_16x16x32_bf16 v[80:83], v[190:193], v[230:233], v[80:83]
	v_mfma_f32_16x16x32_bf16 v[80:83], v[186:189], v[226:229], v[80:83]
	v_mfma_f32_16x16x32_bf16 v[64:67], v[186:189], v[234:237], v[64:67]
	v_mfma_f32_16x16x32_bf16 v[64:67], v[190:193], v[238:241], v[64:67]
	v_mfma_f32_16x16x32_bf16 v[68:71], v[182:185], v[238:241], v[68:71]
	v_mfma_f32_16x16x32_bf16 v[68:71], v[164:167], v[234:237], v[68:71]
	v_mfma_f32_16x16x32_bf16 v[72:75], v[156:159], v[234:237], v[72:75]
	v_mfma_f32_16x16x32_bf16 v[72:75], v[160:163], v[238:241], v[72:75]
	v_mfma_f32_16x16x32_bf16 v[76:79], v[152:155], v[238:241], v[76:79]
	v_mfma_f32_16x16x32_bf16 v[76:79], v[140:143], v[234:237], v[76:79]
	s_barrier
; #define PG8_STAGE(bufoff, gbase, voff) do { _Pragma("unroll") for (int _i = 0; _i < 2; ++_i) \
;         __builtin_amdgcn_global_load_lds((const unsigned*)((const char*)(gbase) + (voff)[_i]), (PG8_LAS unsigned*)(lds + (bufoff) + ldsw + _i * 8192), 16, 0, 0); } while (0)
; #define PG8_LDA(dst, b, h) do { _Pragma("unroll") for (int m = 0; m < 4; ++m) _Pragma("unroll") for (int k = 0; k < 2; ++k) dst[m][k] = *(const PG8_LAS bf16x8*)(lds + PG8_SA(b, h) + aoff + m * 2048 + k * 1024); } while (0)
; #define PG8_LDB(dst, b, h) do { _Pragma("unroll") for (int n = 0; n < 2; ++n) _Pragma("unroll") for (int k = 0; k < 2; ++k) dst[n][k] = *(const PG8_LAS bf16x8*)(lds + PG8_SB(b, h) + boff + n * 2048 + k * 1024); } while (0)
; #define PG8_MMA(ai, bj, At, Bt) do { __builtin_amdgcn_s_setprio(1); _Pragma("unroll") for (int m = 0; m < 4; ++m) _Pragma("unroll") for (int n = 0; n < 2; ++n) _Pragma("unroll") for (int k = 0; k < 2; ++k) \
;         acc[ai][bj][m][n] = __builtin_amdgcn_mfma_f32_16x16x32_bf16(Bt[n][k], At[m][k], acc[ai][bj][m][n], 0, 0, 0); __builtin_amdgcn_s_setprio(0); } while (0)
; template <class Epi, class Sched, bool ALIGN_EPI = false, bool SP2 = false, class Hook = NoHook, bool REVK = false>
; __device__ __forceinline__ void gemm_phase(PG8_LAS unsigned char* lds, const Gemm g, const Sched& S, const Epi& E, const Hook H = Hook()) {
;     ...
;         for (int t = 0; t < nt; t += 2) {
;             if constexpr (Hook::ENABLED) H(acc, t, nt, ui, wr, fr);
;             const bool last = (t == nt - 2);
;             const char* a1 = cA + (long)(t + 1) * kstep;
;             const char* a2 = last ? nA : cA + (long)(t + 2) * kstep; const char* b2 = last ? nB : cB + (long)(t + 2) * kstep;
;             const char* a3 = a2 + kstep; const char* b3 = b2 + kstep;
;             if (last && has_next) S.a_ready(nxt);
;             if constexpr (SP2) {
;             PG8_LDB(B0, 0, 0); PG8_LDB(B1, 0, 1); PG8_SCHED; PG8_LDA(At, 0, 0); PG8_STAGE(PG8_SA(1, 1), a1 + hstep, voffA);
;             PG8_WAIT_V(8); PG8_WAIT_L(0); PG8_BAR; PG8_MMA(0, 0, At, B0); PG8_MMA(0, 1, At, B1); PG8_BAR; PG8_SCHED;
;     ...
;             PG8_LDA(At, 1, 1); PG8_STAGE(PG8_SB(1, 0), b3, voffB); PG8_STAGE(PG8_SB(1, 1), b3 + hstep, voffB); PG8_STAGE(PG8_SA(1, 0), a3, voffA);
;             PG8_WAIT_V(8); PG8_WAIT_L(0); PG8_BAR; PG8_MMA(1, 0, At, B0); PG8_MMA(1, 1, At, B1); PG8_BAR; PG8_SCHED;
	s_setprio 0
	s_add_i32 s26, s46, s10
	v_lshl_add_u64 v[144:145], v[144:145], 0, s[64:65]
	s_mov_b32 m0, s26
	ds_read_b128 v[194:197], v150 offset:49152
	ds_read_b128 v[200:203], v150 offset:50176
	ds_read_b128 v[204:207], v150 offset:51200
	ds_read_b128 v[210:213], v150 offset:52224
	ds_read_b128 v[226:229], v150 offset:53248
	ds_read_b128 v[230:233], v150 offset:54272
	ds_read_b128 v[234:237], v150 offset:55296
	ds_read_b128 v[238:241], v150 offset:56320
	global_load_lds_dwordx4 v[144:145], off
	s_add_i32 m0, s26, 0x2000
	s_add_u32 s20, s20, 0x80080
	v_lshl_add_u64 v[144:145], v[168:169], 0, s[64:65]
	s_addc_u32 s21, s21, 0
	s_add_i32 s26, s56, s10
	global_load_lds_dwordx4 v[144:145], off
	v_lshl_add_u64 v[144:145], s[20:21], 0, v[128:129]
	s_mov_b32 m0, s26
	s_nop 0
	global_load_lds_dwordx4 v[144:145], off
	v_lshl_add_u64 v[144:145], s[20:21], 0, v[130:131]
	s_add_i32 m0, s26, 0x2000
	s_nop 0
	global_load_lds_dwordx4 v[144:145], off
	v_lshl_add_u64 v[144:145], v[214:215], 0, s[64:65]
	s_mov_b32 m0, s36
	s_nop 0
	global_load_lds_dwordx4 v[144:145], off
	v_lshl_add_u64 v[144:145], v[242:243], 0, s[64:65]
	s_mov_b32 m0, s38
	s_nop 0
	global_load_lds_dwordx4 v[144:145], off
	s_waitcnt vmcnt(8)
	s_waitcnt lgkmcnt(0)
	s_setprio 1
	s_barrier
	v_mfma_f32_16x16x32_bf16 v[60:63], v[140:143], v[194:197], v[60:63]
	v_mfma_f32_16x16x32_bf16 v[60:63], v[152:155], v[200:203], v[60:63]
	v_mfma_f32_16x16x32_bf16 v[56:59], v[160:163], v[200:203], v[56:59]
	v_mfma_f32_16x16x32_bf16 v[56:59], v[156:159], v[194:197], v[56:59]
	v_mfma_f32_16x16x32_bf16 v[52:55], v[164:167], v[194:197], v[52:55]
	v_mfma_f32_16x16x32_bf16 v[52:55], v[182:185], v[200:203], v[52:55]
	v_mfma_f32_16x16x32_bf16 v[48:51], v[190:193], v[200:203], v[48:51]
	v_mfma_f32_16x16x32_bf16 v[48:51], v[186:189], v[194:197], v[48:51]
	v_mfma_f32_16x16x32_bf16 v[32:35], v[186:189], v[204:207], v[32:35]
	v_mfma_f32_16x16x32_bf16 v[32:35], v[190:193], v[210:213], v[32:35]
	v_mfma_f32_16x16x32_bf16 v[36:39], v[182:185], v[210:213], v[36:39]
	v_mfma_f32_16x16x32_bf16 v[36:39], v[164:167], v[204:207], v[36:39]
	v_mfma_f32_16x16x32_bf16 v[40:43], v[156:159], v[204:207], v[40:43]
	v_mfma_f32_16x16x32_bf16 v[40:43], v[160:163], v[210:213], v[40:43]
	v_mfma_f32_16x16x32_bf16 v[44:47], v[152:155], v[210:213], v[44:47]
	v_mfma_f32_16x16x32_bf16 v[44:47], v[140:143], v[204:207], v[44:47]
	v_mfma_f32_16x16x32_bf16 v[28:31], v[140:143], v[226:229], v[28:31]
	v_mfma_f32_16x16x32_bf16 v[28:31], v[152:155], v[230:233], v[28:31]
	v_mfma_f32_16x16x32_bf16 v[24:27], v[160:163], v[230:233], v[24:27]
	v_mfma_f32_16x16x32_bf16 v[24:27], v[156:159], v[226:229], v[24:27]
	v_mfma_f32_16x16x32_bf16 v[20:23], v[164:167], v[226:229], v[20:23]
	v_mfma_f32_16x16x32_bf16 v[20:23], v[182:185], v[230:233], v[20:23]
	v_mfma_f32_16x16x32_bf16 v[16:19], v[190:193], v[230:233], v[16:19]
	v_mfma_f32_16x16x32_bf16 v[16:19], v[186:189], v[226:229], v[16:19]
	v_mfma_f32_16x16x32_bf16 v[0:3], v[186:189], v[234:237], v[0:3]
	v_mfma_f32_16x16x32_bf16 v[0:3], v[190:193], v[238:241], v[0:3]
	v_mfma_f32_16x16x32_bf16 v[4:7], v[182:185], v[238:241], v[4:7]
	v_mfma_f32_16x16x32_bf16 v[4:7], v[164:167], v[234:237], v[4:7]
	v_mfma_f32_16x16x32_bf16 v[8:11], v[156:159], v[234:237], v[8:11]
	v_mfma_f32_16x16x32_bf16 v[8:11], v[160:163], v[238:241], v[8:11]
	v_mfma_f32_16x16x32_bf16 v[12:15], v[152:155], v[238:241], v[12:15]
	v_mfma_f32_16x16x32_bf16 v[12:15], v[140:143], v[234:237], v[12:15]
	s_barrier
	s_setprio 0
	s_add_i32 s53, s53, 2
	s_add_u32 s22, s22, 0x100
	s_addc_u32 s23, s23, 0
	s_add_u32 s47, s47, 0x100
	s_addc_u32 s51, s51, 0
	s_cmp_gt_u32 s53, 29
.LBB0_582:
	s_add_u32 s20, s22, 0xfff80080
	s_addc_u32 s21, s23, -1
	s_add_i32 s46, 0, 0x10000
	s_cmp_eq_u32 s53, 28
	s_cselect_b32 s27, s41, s21
	s_cselect_b32 s26, s42, s20
	v_add_u32_e32 v144, s46, v147
	s_cselect_b32 s21, s43, s51
	s_cselect_b32 s20, s44, s47
	s_add_i32 s58, 0, 0x14000
	ds_read_b128 v[140:143], v144
	ds_read_b128 v[152:155], v144 offset:1024
	ds_read_b128 v[156:159], v144 offset:2048
	ds_read_b128 v[160:163], v144 offset:3072
	v_add_u32_e32 v144, s58, v147
	ds_read_b128 v[164:167], v144
	ds_read_b128 v[182:185], v144 offset:1024
	ds_read_b128 v[186:189], v144 offset:2048
	ds_read_b128 v[190:193], v144 offset:3072
	v_lshl_add_u64 v[144:145], s[22:23], 0, v[136:137]
	s_add_i32 m0, s30, 0xc000
	ds_read_b128 v[194:197], v150
	ds_read_b128 v[200:203], v150 offset:1024
	ds_read_b128 v[204:207], v150 offset:2048
	ds_read_b128 v[210:213], v150 offset:3072
	ds_read_b128 v[226:229], v150 offset:4096
	ds_read_b128 v[230:233], v150 offset:5120
	ds_read_b128 v[234:237], v150 offset:6144
	ds_read_b128 v[238:241], v150 offset:7168
	global_load_lds_dwordx4 v[144:145], off
	v_lshl_add_u64 v[144:145], s[22:23], 0, v[138:139]
	s_add_i32 m0, s30, 0xe000
	s_nop 0
	global_load_lds_dwordx4 v[144:145], off
	s_waitcnt vmcnt(8)
	s_waitcnt lgkmcnt(0)
	s_setprio 1
	s_barrier
; #define PG8_STAGE(bufoff, gbase, voff) do { _Pragma("unroll") for (int _i = 0; _i < 2; ++_i) \
;         __builtin_amdgcn_global_load_lds((const unsigned*)((const char*)(gbase) + (voff)[_i]), (PG8_LAS unsigned*)(lds + (bufoff) + ldsw + _i * 8192), 16, 0, 0); } while (0)
; #define PG8_LDA(dst, b, h) do { _Pragma("unroll") for (int m = 0; m < 4; ++m) _Pragma("unroll") for (int k = 0; k < 2; ++k) dst[m][k] = *(const PG8_LAS bf16x8*)(lds + PG8_SA(b, h) + aoff + m * 2048 + k * 1024); } while (0)
; #define PG8_LDB(dst, b, h) do { _Pragma("unroll") for (int n = 0; n < 2; ++n) _Pragma("unroll") for (int k = 0; k < 2; ++k) dst[n][k] = *(const PG8_LAS bf16x8*)(lds + PG8_SB(b, h) + boff + n * 2048 + k * 1024); } while (0)
; #define PG8_MMA(ai, bj, At, Bt) do { __builtin_amdgcn_s_setprio(1); _Pragma("unroll") for (int m = 0; m < 4; ++m) _Pragma("unroll") for (int n = 0; n < 2; ++n) _Pragma("unroll") for (int k = 0; k < 2; ++k) \
;         acc[ai][bj][m][n] = __builtin_amdgcn_mfma_f32_16x16x32_bf16(Bt[n][k], At[m][k], acc[ai][bj][m][n], 0, 0, 0); __builtin_amdgcn_s_setprio(0); } while (0)
; #define PG8_WAIT_V(n) asm volatile("s_waitcnt vmcnt(" #n ")" ::: "memory")
; #define PG8_WAIT_L(n) asm volatile("s_waitcnt lgkmcnt(" #n ")" ::: "memory")
; #define PG8_BAR __builtin_amdgcn_s_barrier()
; #define PG8_SCHED __builtin_amdgcn_sched_barrier(0)
; template <class Epi, class Sched, bool ALIGN_EPI = false, bool SP2 = false, class Hook = NoHook, bool REVK = false>
; __device__ __forceinline__ void gemm_phase(PG8_LAS unsigned char* lds, const Gemm g, const Sched& S, const Epi& E, const Hook H = Hook()) {
;     ...
;             PG8_LDB(B0, 0, 0); PG8_LDB(B1, 0, 1); PG8_SCHED; PG8_LDA(At, 0, 0); PG8_STAGE(PG8_SA(1, 1), a1 + hstep, voffA);
;             PG8_WAIT_V(8); PG8_WAIT_L(0); PG8_BAR; PG8_MMA(0, 0, At, B0); PG8_MMA(0, 1, At, B1); PG8_BAR; PG8_SCHED;
;             PG8_LDA(At, 0, 1); PG8_STAGE(PG8_SB(0, 0), b2, voffB); PG8_STAGE(PG8_SB(0, 1), b2 + hstep, voffB); PG8_STAGE(PG8_SA(0, 0), a2, voffA);
;             PG8_WAIT_V(8); PG8_WAIT_L(0); PG8_BAR; PG8_MMA(1, 0, At, B0); PG8_MMA(1, 1, At, B1); PG8_BAR; PG8_SCHED;
;             PG8_LDB(B0, 1, 0); PG8_LDB(B1, 1, 1); PG8_SCHED; PG8_LDA(At, 1, 0); PG8_STAGE(PG8_SA(0, 1), a2 + hstep, voffA);
	v_mfma_f32_16x16x32_bf16 v[124:127], v[140:143], v[194:197], v[124:127]
	v_mfma_f32_16x16x32_bf16 v[124:127], v[152:155], v[200:203], v[124:127]
	v_mfma_f32_16x16x32_bf16 v[120:123], v[160:163], v[200:203], v[120:123]
	v_mfma_f32_16x16x32_bf16 v[120:123], v[156:159], v[194:197], v[120:123]
	v_mfma_f32_16x16x32_bf16 v[116:119], v[164:167], v[194:197], v[116:119]
	v_mfma_f32_16x16x32_bf16 v[116:119], v[182:185], v[200:203], v[116:119]
	v_mfma_f32_16x16x32_bf16 v[112:115], v[190:193], v[200:203], v[112:115]
	v_mfma_f32_16x16x32_bf16 v[112:115], v[186:189], v[194:197], v[112:115]
	v_mfma_f32_16x16x32_bf16 v[96:99], v[186:189], v[204:207], v[96:99]
	v_mfma_f32_16x16x32_bf16 v[96:99], v[190:193], v[210:213], v[96:99]
	v_mfma_f32_16x16x32_bf16 v[100:103], v[182:185], v[210:213], v[100:103]
	v_mfma_f32_16x16x32_bf16 v[100:103], v[164:167], v[204:207], v[100:103]
	v_mfma_f32_16x16x32_bf16 v[104:107], v[156:159], v[204:207], v[104:107]
	v_mfma_f32_16x16x32_bf16 v[104:107], v[160:163], v[210:213], v[104:107]
	v_mfma_f32_16x16x32_bf16 v[108:111], v[152:155], v[210:213], v[108:111]
	v_mfma_f32_16x16x32_bf16 v[108:111], v[140:143], v[204:207], v[108:111]
	v_mfma_f32_16x16x32_bf16 v[92:95], v[140:143], v[226:229], v[92:95]
	v_mfma_f32_16x16x32_bf16 v[92:95], v[152:155], v[230:233], v[92:95]
	v_mfma_f32_16x16x32_bf16 v[88:91], v[160:163], v[230:233], v[88:91]
	v_mfma_f32_16x16x32_bf16 v[88:91], v[156:159], v[226:229], v[88:91]
	v_mfma_f32_16x16x32_bf16 v[84:87], v[164:167], v[226:229], v[84:87]
	v_mfma_f32_16x16x32_bf16 v[84:87], v[182:185], v[230:233], v[84:87]
	v_mfma_f32_16x16x32_bf16 v[80:83], v[190:193], v[230:233], v[80:83]
	v_mfma_f32_16x16x32_bf16 v[80:83], v[186:189], v[226:229], v[80:83]
	v_mfma_f32_16x16x32_bf16 v[64:67], v[186:189], v[234:237], v[64:67]
	v_mfma_f32_16x16x32_bf16 v[64:67], v[190:193], v[238:241], v[64:67]
	v_mfma_f32_16x16x32_bf16 v[68:71], v[182:185], v[238:241], v[68:71]
	v_mfma_f32_16x16x32_bf16 v[68:71], v[164:167], v[234:237], v[68:71]
	v_mfma_f32_16x16x32_bf16 v[72:75], v[156:159], v[234:237], v[72:75]
	v_mfma_f32_16x16x32_bf16 v[72:75], v[160:163], v[238:241], v[72:75]
	v_mfma_f32_16x16x32_bf16 v[76:79], v[152:155], v[238:241], v[76:79]
	v_mfma_f32_16x16x32_bf16 v[76:79], v[140:143], v[234:237], v[76:79]
	s_barrier
	s_setprio 0
	s_add_i32 s46, s46, s10
	v_lshl_add_u64 v[144:145], s[20:21], 0, v[128:129]
	s_mov_b32 m0, s46
	ds_read_b128 v[194:197], v150 offset:16384
	ds_read_b128 v[200:203], v150 offset:17408
	ds_read_b128 v[204:207], v150 offset:18432
	ds_read_b128 v[210:213], v150 offset:19456
	ds_read_b128 v[226:229], v150 offset:20480
	ds_read_b128 v[230:233], v150 offset:21504
	ds_read_b128 v[234:237], v150 offset:22528
	ds_read_b128 v[238:241], v150 offset:23552
	global_load_lds_dwordx4 v[144:145], off
	s_add_i32 m0, s46, 0x2000
	s_add_u32 s56, s20, 0x80000
	v_lshl_add_u64 v[168:169], s[20:21], 0, v[130:131]
	s_addc_u32 s57, s21, 0
	s_add_i32 s46, s58, s10
	global_load_lds_dwordx4 v[168:169], off
	v_lshl_add_u64 v[214:215], s[56:57], 0, v[128:129]
	s_mov_b32 m0, s46
	v_lshl_add_u64 v[242:243], s[26:27], 0, v[132:133]
	global_load_lds_dwordx4 v[214:215], off
	v_lshl_add_u64 v[214:215], s[56:57], 0, v[130:131]
	s_add_i32 m0, s46, 0x2000
	s_nop 0
	global_load_lds_dwordx4 v[214:215], off
	v_lshl_add_u64 v[214:215], s[26:27], 0, v[134:135]
	s_mov_b32 m0, s30
	s_nop 0
	global_load_lds_dwordx4 v[214:215], off
	s_mov_b32 m0, s31
	s_nop 0
	global_load_lds_dwordx4 v[242:243], off
	s_waitcnt vmcnt(8)
	s_waitcnt lgkmcnt(0)
	s_setprio 1
	s_barrier
	v_mfma_f32_16x16x32_bf16 v[60:63], v[140:143], v[194:197], v[60:63]
	v_mfma_f32_16x16x32_bf16 v[60:63], v[152:155], v[200:203], v[60:63]
	v_mfma_f32_16x16x32_bf16 v[56:59], v[160:163], v[200:203], v[56:59]
	v_mfma_f32_16x16x32_bf16 v[56:59], v[156:159], v[194:197], v[56:59]
	v_mfma_f32_16x16x32_bf16 v[52:55], v[164:167], v[194:197], v[52:55]
	v_mfma_f32_16x16x32_bf16 v[52:55], v[182:185], v[200:203], v[52:55]
	v_mfma_f32_16x16x32_bf16 v[48:51], v[190:193], v[200:203], v[48:51]
	v_mfma_f32_16x16x32_bf16 v[48:51], v[186:189], v[194:197], v[48:51]
	v_mfma_f32_16x16x32_bf16 v[32:35], v[186:189], v[204:207], v[32:35]
	v_mfma_f32_16x16x32_bf16 v[32:35], v[190:193], v[210:213], v[32:35]
	v_mfma_f32_16x16x32_bf16 v[36:39], v[182:185], v[210:213], v[36:39]
	v_mfma_f32_16x16x32_bf16 v[36:39], v[164:167], v[204:207], v[36:39]
	v_mfma_f32_16x16x32_bf16 v[40:43], v[156:159], v[204:207], v[40:43]
	v_mfma_f32_16x16x32_bf16 v[40:43], v[160:163], v[210:213], v[40:43]
	v_mfma_f32_16x16x32_bf16 v[44:47], v[152:155], v[210:213], v[44:47]
	v_mfma_f32_16x16x32_bf16 v[44:47], v[140:143], v[204:207], v[44:47]
	v_mfma_f32_16x16x32_bf16 v[28:31], v[140:143], v[226:229], v[28:31]
	v_mfma_f32_16x16x32_bf16 v[28:31], v[152:155], v[230:233], v[28:31]
	v_mfma_f32_16x16x32_bf16 v[24:27], v[160:163], v[230:233], v[24:27]
	v_mfma_f32_16x16x32_bf16 v[24:27], v[156:159], v[226:229], v[24:27]
	v_mfma_f32_16x16x32_bf16 v[20:23], v[164:167], v[226:229], v[20:23]
	v_mfma_f32_16x16x32_bf16 v[20:23], v[182:185], v[230:233], v[20:23]
	v_mfma_f32_16x16x32_bf16 v[16:19], v[190:193], v[230:233], v[16:19]
	v_mfma_f32_16x16x32_bf16 v[16:19], v[186:189], v[226:229], v[16:19]
	v_mfma_f32_16x16x32_bf16 v[0:3], v[186:189], v[234:237], v[0:3]
	v_mfma_f32_16x16x32_bf16 v[0:3], v[190:193], v[238:241], v[0:3]
	v_mfma_f32_16x16x32_bf16 v[4:7], v[182:185], v[238:241], v[4:7]
	v_mfma_f32_16x16x32_bf16 v[4:7], v[164:167], v[234:237], v[4:7]
	v_mfma_f32_16x16x32_bf16 v[8:11], v[156:159], v[234:237], v[8:11]
	v_mfma_f32_16x16x32_bf16 v[8:11], v[160:163], v[238:241], v[8:11]
	v_mfma_f32_16x16x32_bf16 v[12:15], v[152:155], v[238:241], v[12:15]
	v_mfma_f32_16x16x32_bf16 v[12:15], v[140:143], v[234:237], v[12:15]
	s_barrier
; #define PG8_STAGE(bufoff, gbase, voff) do { _Pragma("unroll") for (int _i = 0; _i < 2; ++_i) \
;         __builtin_amdgcn_global_load_lds((const unsigned*)((const char*)(gbase) + (voff)[_i]), (PG8_LAS unsigned*)(lds + (bufoff) + ldsw + _i * 8192), 16, 0, 0); } while (0)
; #define PG8_LDA(dst, b, h) do { _Pragma("unroll") for (int m = 0; m < 4; ++m) _Pragma("unroll") for (int k = 0; k < 2; ++k) dst[m][k] = *(const PG8_LAS bf16x8*)(lds + PG8_SA(b, h) + aoff + m * 2048 + k * 1024); } while (0)
; #define PG8_LDB(dst, b, h) do { _Pragma("unroll") for (int n = 0; n < 2; ++n) _Pragma("unroll") for (int k = 0; k < 2; ++k) dst[n][k] = *(const PG8_LAS bf16x8*)(lds + PG8_SB(b, h) + boff + n * 2048 + k * 1024); } while (0)
; #define PG8_MMA(ai, bj, At, Bt) do { __builtin_amdgcn_s_setprio(1); _Pragma("unroll") for (int m = 0; m < 4; ++m) _Pragma("unroll") for (int n = 0; n < 2; ++n) _Pragma("unroll") for (int k = 0; k < 2; ++k) \
;         acc[ai][bj][m][n] = __builtin_amdgcn_mfma_f32_16x16x32_bf16(Bt[n][k], At[m][k], acc[ai][bj][m][n], 0, 0, 0); __builtin_amdgcn_s_setprio(0); } while (0)
; #define PG8_WAIT_V(n) asm volatile("s_waitcnt vmcnt(" #n ")" ::: "memory")
; #define PG8_WAIT_L(n) asm volatile("s_waitcnt lgkmcnt(" #n ")" ::: "memory")
; #define PG8_BAR __builtin_amdgcn_s_barrier()
; #define PG8_SCHED __builtin_amdgcn_sched_barrier(0)
; template <class Epi, class Sched, bool ALIGN_EPI = false, bool SP2 = false, class Hook = NoHook, bool REVK = false>
; __device__ __forceinline__ void gemm_phase(PG8_LAS unsigned char* lds, const Gemm g, const Sched& S, const Epi& E, const Hook H = Hook()) {
;     ...
;             PG8_LDB(B0, 1, 0); PG8_LDB(B1, 1, 1); PG8_SCHED; PG8_LDA(At, 1, 0); PG8_STAGE(PG8_SA(0, 1), a2 + hstep, voffA);
;             PG8_WAIT_V(8); PG8_WAIT_L(0); PG8_BAR; PG8_MMA(0, 0, At, B0); PG8_MMA(0, 1, At, B1); PG8_BAR; PG8_SCHED;
	s_setprio 0
	s_add_i32 s46, 0, 0x18000
	v_add_u32_e32 v151, s46, v147
	s_add_i32 s56, 0, 0x1c000
	ds_read_b128 v[140:143], v151
	ds_read_b128 v[152:155], v151 offset:1024
	ds_read_b128 v[156:159], v151 offset:2048
	ds_read_b128 v[160:163], v151 offset:3072
	v_add_u32_e32 v151, s56, v147
	ds_read_b128 v[164:167], v151
	ds_read_b128 v[182:185], v151 offset:1024
	ds_read_b128 v[186:189], v151 offset:2048
	ds_read_b128 v[190:193], v151 offset:3072
	s_add_u32 s26, s26, 0x80000
	s_addc_u32 s27, s27, 0
	s_mov_b32 m0, s34
	v_lshl_add_u64 v[244:245], s[26:27], 0, v[134:135]
	ds_read_b128 v[194:197], v150 offset:32768
	ds_read_b128 v[200:203], v150 offset:33792
	ds_read_b128 v[204:207], v150 offset:34816
	ds_read_b128 v[210:213], v150 offset:35840
	ds_read_b128 v[226:229], v150 offset:36864
	ds_read_b128 v[230:233], v150 offset:37888
	ds_read_b128 v[234:237], v150 offset:38912
	ds_read_b128 v[238:241], v150 offset:39936
	global_load_lds_dwordx4 v[244:245], off
	v_lshl_add_u64 v[244:245], s[26:27], 0, v[132:133]
	s_mov_b32 m0, s35
	s_nop 0
	global_load_lds_dwordx4 v[244:245], off
	s_waitcnt vmcnt(8)
	s_waitcnt lgkmcnt(0)
	s_setprio 1
	s_barrier
	v_mfma_f32_16x16x32_bf16 v[124:127], v[140:143], v[194:197], v[124:127]
	v_mfma_f32_16x16x32_bf16 v[124:127], v[152:155], v[200:203], v[124:127]
	v_mfma_f32_16x16x32_bf16 v[120:123], v[160:163], v[200:203], v[120:123]
	v_mfma_f32_16x16x32_bf16 v[120:123], v[156:159], v[194:197], v[120:123]
	v_mfma_f32_16x16x32_bf16 v[116:119], v[164:167], v[194:197], v[116:119]
	v_mfma_f32_16x16x32_bf16 v[116:119], v[182:185], v[200:203], v[116:119]
	v_mfma_f32_16x16x32_bf16 v[112:115], v[190:193], v[200:203], v[112:115]
	v_mfma_f32_16x16x32_bf16 v[112:115], v[186:189], v[194:197], v[112:115]
	v_mfma_f32_16x16x32_bf16 v[96:99], v[186:189], v[204:207], v[96:99]
	v_mfma_f32_16x16x32_bf16 v[96:99], v[190:193], v[210:213], v[96:99]
	v_mfma_f32_16x16x32_bf16 v[100:103], v[182:185], v[210:213], v[100:103]
	v_mfma_f32_16x16x32_bf16 v[100:103], v[164:167], v[204:207], v[100:103]
	v_mfma_f32_16x16x32_bf16 v[104:107], v[156:159], v[204:207], v[104:107]
	v_mfma_f32_16x16x32_bf16 v[104:107], v[160:163], v[210:213], v[104:107]
	v_mfma_f32_16x16x32_bf16 v[108:111], v[152:155], v[210:213], v[108:111]
	v_mfma_f32_16x16x32_bf16 v[108:111], v[140:143], v[204:207], v[108:111]
	v_mfma_f32_16x16x32_bf16 v[92:95], v[140:143], v[226:229], v[92:95]
	v_mfma_f32_16x16x32_bf16 v[92:95], v[152:155], v[230:233], v[92:95]
	v_mfma_f32_16x16x32_bf16 v[88:91], v[160:163], v[230:233], v[88:91]
	v_mfma_f32_16x16x32_bf16 v[88:91], v[156:159], v[226:229], v[88:91]
	v_mfma_f32_16x16x32_bf16 v[84:87], v[164:167], v[226:229], v[84:87]
	v_mfma_f32_16x16x32_bf16 v[84:87], v[182:185], v[230:233], v[84:87]
	v_mfma_f32_16x16x32_bf16 v[80:83], v[190:193], v[230:233], v[80:83]
	v_mfma_f32_16x16x32_bf16 v[80:83], v[186:189], v[226:229], v[80:83]
	v_mfma_f32_16x16x32_bf16 v[64:67], v[186:189], v[234:237], v[64:67]
	v_mfma_f32_16x16x32_bf16 v[64:67], v[190:193], v[238:241], v[64:67]
	v_mfma_f32_16x16x32_bf16 v[68:71], v[182:185], v[238:241], v[68:71]
	v_mfma_f32_16x16x32_bf16 v[68:71], v[164:167], v[234:237], v[68:71]
	v_mfma_f32_16x16x32_bf16 v[72:75], v[156:159], v[234:237], v[72:75]
	v_mfma_f32_16x16x32_bf16 v[72:75], v[160:163], v[238:241], v[72:75]
	v_mfma_f32_16x16x32_bf16 v[76:79], v[152:155], v[238:241], v[76:79]
	v_mfma_f32_16x16x32_bf16 v[76:79], v[140:143], v[234:237], v[76:79]
	s_barrier
; #define PG8_STAGE(bufoff, gbase, voff) do { _Pragma("unroll") for (int _i = 0; _i < 2; ++_i) \
;         __builtin_amdgcn_global_load_lds((const unsigned*)((const char*)(gbase) + (voff)[_i]), (PG8_LAS unsigned*)(lds + (bufoff) + ldsw + _i * 8192), 16, 0, 0); } while (0)
; #define PG8_LDA(dst, b, h) do { _Pragma("unroll") for (int m = 0; m < 4; ++m) _Pragma("unroll") for (int k = 0; k < 2; ++k) dst[m][k] = *(const PG8_LAS bf16x8*)(lds + PG8_SA(b, h) + aoff + m * 2048 + k * 1024); } while (0)
; #define PG8_MMA(ai, bj, At, Bt) do { __builtin_amdgcn_s_setprio(1); _Pragma("unroll") for (int m = 0; m < 4; ++m) _Pragma("unroll") for (int n = 0; n < 2; ++n) _Pragma("unroll") for (int k = 0; k < 2; ++k) \
;         acc[ai][bj][m][n] = __builtin_amdgcn_mfma_f32_16x16x32_bf16(Bt[n][k], At[m][k], acc[ai][bj][m][n], 0, 0, 0); __builtin_amdgcn_s_setprio(0); } while (0)
; #define PG8_WAIT_V(n) asm volatile("s_waitcnt vmcnt(" #n ")" ::: "memory")
; #define PG8_WAIT_L(n) asm volatile("s_waitcnt lgkmcnt(" #n ")" ::: "memory")
; #define PG8_BAR __builtin_amdgcn_s_barrier()
; #define PG8_SCHED __builtin_amdgcn_sched_barrier(0)
; template <class Epi, class Sched, bool ALIGN_EPI = false, bool SP2 = false, class Hook = NoHook, bool REVK = false>
; __device__ __forceinline__ void gemm_phase(PG8_LAS unsigned char* lds, const Gemm g, const Sched& S, const Epi& E, const Hook H = Hook()) {
;     ...
;             PG8_LDA(At, 1, 1); PG8_STAGE(PG8_SB(1, 0), b3, voffB); PG8_STAGE(PG8_SB(1, 1), b3 + hstep, voffB); PG8_STAGE(PG8_SA(1, 0), a3, voffA);
;             PG8_WAIT_V(8); PG8_WAIT_L(0); PG8_BAR; PG8_MMA(1, 0, At, B0); PG8_MMA(1, 1, At, B1); PG8_BAR; PG8_SCHED;
;     ...
;         if constexpr (ALIGN_EPI) { if (wr == 0) PG8_BAR; }
	s_setprio 0
	s_add_i32 s26, s46, s10
	v_lshl_add_u64 v[144:145], v[144:145], 0, s[64:65]
	s_mov_b32 m0, s26
	ds_read_b128 v[194:197], v150 offset:49152
	ds_read_b128 v[200:203], v150 offset:50176
	ds_read_b128 v[204:207], v150 offset:51200
	ds_read_b128 v[210:213], v150 offset:52224
	ds_read_b128 v[226:229], v150 offset:53248
	ds_read_b128 v[230:233], v150 offset:54272
	ds_read_b128 v[234:237], v150 offset:55296
	ds_read_b128 v[238:241], v150 offset:56320
	global_load_lds_dwordx4 v[144:145], off
	s_add_i32 m0, s26, 0x2000
	s_add_u32 s20, s20, 0x80080
	v_lshl_add_u64 v[144:145], v[168:169], 0, s[64:65]
	s_addc_u32 s21, s21, 0
	s_add_i32 s26, s56, s10
	global_load_lds_dwordx4 v[144:145], off
	v_lshl_add_u64 v[144:145], s[20:21], 0, v[128:129]
	s_mov_b32 m0, s26
	s_nop 0
	global_load_lds_dwordx4 v[144:145], off
	v_lshl_add_u64 v[144:145], s[20:21], 0, v[130:131]
	s_add_i32 m0, s26, 0x2000
	s_nop 0
	global_load_lds_dwordx4 v[144:145], off
	v_lshl_add_u64 v[144:145], v[214:215], 0, s[64:65]
	s_mov_b32 m0, s36
	s_nop 0
	global_load_lds_dwordx4 v[144:145], off
	v_lshl_add_u64 v[144:145], v[242:243], 0, s[64:65]
	s_mov_b32 m0, s38
	s_nop 0
	global_load_lds_dwordx4 v[144:145], off
	s_waitcnt vmcnt(8)
	s_waitcnt lgkmcnt(0)
	s_setprio 1
	s_barrier
	v_mfma_f32_16x16x32_bf16 v[60:63], v[140:143], v[194:197], v[60:63]
	v_mfma_f32_16x16x32_bf16 v[60:63], v[152:155], v[200:203], v[60:63]
	v_mfma_f32_16x16x32_bf16 v[56:59], v[160:163], v[200:203], v[56:59]
	v_mfma_f32_16x16x32_bf16 v[56:59], v[156:159], v[194:197], v[56:59]
	v_mfma_f32_16x16x32_bf16 v[52:55], v[164:167], v[194:197], v[52:55]
	v_mfma_f32_16x16x32_bf16 v[52:55], v[182:185], v[200:203], v[52:55]
	v_mfma_f32_16x16x32_bf16 v[48:51], v[190:193], v[200:203], v[48:51]
	v_mfma_f32_16x16x32_bf16 v[48:51], v[186:189], v[194:197], v[48:51]
	v_mfma_f32_16x16x32_bf16 v[32:35], v[186:189], v[204:207], v[32:35]
	v_mfma_f32_16x16x32_bf16 v[32:35], v[190:193], v[210:213], v[32:35]
	v_mfma_f32_16x16x32_bf16 v[36:39], v[182:185], v[210:213], v[36:39]
	v_mfma_f32_16x16x32_bf16 v[36:39], v[164:167], v[204:207], v[36:39]
	v_mfma_f32_16x16x32_bf16 v[40:43], v[156:159], v[204:207], v[40:43]
	v_mfma_f32_16x16x32_bf16 v[40:43], v[160:163], v[210:213], v[40:43]
	v_mfma_f32_16x16x32_bf16 v[44:47], v[152:155], v[210:213], v[44:47]
	v_mfma_f32_16x16x32_bf16 v[44:47], v[140:143], v[204:207], v[44:47]
	v_mfma_f32_16x16x32_bf16 v[28:31], v[140:143], v[226:229], v[28:31]
	v_mfma_f32_16x16x32_bf16 v[28:31], v[152:155], v[230:233], v[28:31]
	v_mfma_f32_16x16x32_bf16 v[24:27], v[160:163], v[230:233], v[24:27]
	v_mfma_f32_16x16x32_bf16 v[24:27], v[156:159], v[226:229], v[24:27]
	v_mfma_f32_16x16x32_bf16 v[20:23], v[164:167], v[226:229], v[20:23]
	v_mfma_f32_16x16x32_bf16 v[20:23], v[182:185], v[230:233], v[20:23]
	v_mfma_f32_16x16x32_bf16 v[16:19], v[190:193], v[230:233], v[16:19]
	v_mfma_f32_16x16x32_bf16 v[16:19], v[186:189], v[226:229], v[16:19]
	v_mfma_f32_16x16x32_bf16 v[0:3], v[186:189], v[234:237], v[0:3]
	v_mfma_f32_16x16x32_bf16 v[0:3], v[190:193], v[238:241], v[0:3]
	v_mfma_f32_16x16x32_bf16 v[4:7], v[182:185], v[238:241], v[4:7]
	v_mfma_f32_16x16x32_bf16 v[4:7], v[164:167], v[234:237], v[4:7]
	v_mfma_f32_16x16x32_bf16 v[8:11], v[156:159], v[234:237], v[8:11]
	v_mfma_f32_16x16x32_bf16 v[8:11], v[160:163], v[238:241], v[8:11]
	v_mfma_f32_16x16x32_bf16 v[12:15], v[152:155], v[238:241], v[12:15]
	v_mfma_f32_16x16x32_bf16 v[12:15], v[140:143], v[234:237], v[12:15]
	s_barrier
	s_setprio 0
	s_add_i32 s53, s53, 2
	s_add_u32 s22, s22, 0x100
	s_addc_u32 s23, s23, 0
	s_add_u32 s47, s47, 0x100
	s_addc_u32 s51, s51, 0
	s_cmp_gt_u32 s53, 29
	s_cbranch_scc0 .LBB0_582
	s_and_b64 vcc, exec, s[82:83]
	s_cbranch_vccz .LBB0_585
	s_barrier

; #define PG8_STAGE(bufoff, gbase, voff) do { _Pragma("unroll") for (int _i = 0; _i < 2; ++_i) \
;         __builtin_amdgcn_global_load_lds((const unsigned*)((const char*)(gbase) + (voff)[_i]), (PG8_LAS unsigned*)(lds + (bufoff) + ldsw + _i * 8192), 16, 0, 0); } while (0)
; #define PG8_LDA(dst, b, h) do { _Pragma("unroll") for (int m = 0; m < 4; ++m) _Pragma("unroll") for (int k = 0; k < 2; ++k) dst[m][k] = *(const PG8_LAS bf16x8*)(lds + PG8_SA(b, h) + aoff + m * 2048 + k * 1024); } while (0)
; #define PG8_LDB(dst, b, h) do { _Pragma("unroll") for (int n = 0; n < 2; ++n) _Pragma("unroll") for (int k = 0; k < 2; ++k) dst[n][k] = *(const PG8_LAS bf16x8*)(lds + PG8_SB(b, h) + boff + n * 2048 + k * 1024); } while (0)
; #define PG8_MMA(ai, bj, At, Bt) do { __builtin_amdgcn_s_setprio(1); _Pragma("unroll") for (int m = 0; m < 4; ++m) _Pragma("unroll") for (int n = 0; n < 2; ++n) _Pragma("unroll") for (int k = 0; k < 2; ++k) \
;         acc[ai][bj][m][n] = __builtin_amdgcn_mfma_f32_16x16x32_bf16(Bt[n][k], At[m][k], acc[ai][bj][m][n], 0, 0, 0); __builtin_amdgcn_s_setprio(0); } while (0)
; #define PG8_WAIT_V(n) asm volatile("s_waitcnt vmcnt(" #n ")" ::: "memory")
; #define PG8_BAR __builtin_amdgcn_s_barrier()
; template <class Epi, class Sched, bool ALIGN_EPI = false, bool SP2 = false, class Hook = NoHook, bool REVK = false>
; __device__ __forceinline__ void gemm_phase(PG8_LAS unsigned char* lds, const Gemm g, const Sched& S, const Epi& E, const Hook H = Hook()) {
;     ...
;             const bool last = (t == nt - 2);
;             const char* a1 = cA + (long)(t + 1) * kstep;
;             const char* a2 = last ? nA : cA + (long)(t + 2) * kstep; const char* b2 = last ? nB : cB + (long)(t + 2) * kstep;
;             const char* a3 = a2 + kstep; const char* b3 = b2 + kstep;
;             if (last && has_next) S.a_ready(nxt);
;             if constexpr (SP2) {
;             PG8_LDB(B0, 0, 0); PG8_LDB(B1, 0, 1); PG8_SCHED; PG8_LDA(At, 0, 0); PG8_STAGE(PG8_SA(1, 1), a1 + hstep, voffA);
;             PG8_WAIT_V(8); PG8_WAIT_L(0); PG8_BAR; PG8_MMA(0, 0, At, B0); PG8_MMA(0, 1, At, B1); PG8_BAR; PG8_SCHED;
;             PG8_LDA(At, 0, 1); PG8_STAGE(PG8_SB(0, 0), b2, voffB); PG8_STAGE(PG8_SB(0, 1), b2 + hstep, voffB); PG8_STAGE(PG8_SA(0, 0), a2, voffA);
;             PG8_WAIT_V(8); PG8_WAIT_L(0); PG8_BAR; PG8_MMA(1, 0, At, B0); PG8_MMA(1, 1, At, B1); PG8_BAR; PG8_SCHED;
.LBB0_654:
	s_or_b32 s54, s42, 1
	s_lshl_b64 s[46:47], s[54:55], 7
	s_sub_u32 s44, 0, s46
	s_subb_u32 s46, 0, s47
	s_add_u32 s44, s94, s44
	s_addc_u32 s47, s95, s46
	s_add_i32 s51, 0, 0x10000
	s_add_i32 s53, 0, 0x14000
	v_add_u32_e32 v142, s51, v195
	v_add_u32_e32 v158, s53, v195
	ds_read_b128 v[124:127], v142
	ds_read_b128 v[134:137], v142 offset:1024
	ds_read_b128 v[138:141], v142 offset:2048
	ds_read_b128 v[142:145], v142 offset:3072
	ds_read_b128 v[146:149], v158
	ds_read_b128 v[150:153], v158 offset:1024
	ds_read_b128 v[154:157], v158 offset:2048
	ds_read_b128 v[158:161], v158 offset:3072
	s_add_u32 s46, s44, 0x200000
	s_addc_u32 s47, s47, 0
	v_lshl_add_u64 v[168:169], s[46:47], 0, v[166:167]
	s_add_i32 m0, s34, 0xc000
	ds_read_b128 v[182:185], v197
	ds_read_b128 v[186:189], v197 offset:1024
	ds_read_b128 v[190:193], v197 offset:2048
	ds_read_b128 v[200:203], v197 offset:3072
	ds_read_b128 v[204:207], v197 offset:4096
	ds_read_b128 v[210:213], v197 offset:5120
	ds_read_b128 v[226:229], v197 offset:6144
	ds_read_b128 v[230:233], v197 offset:7168
	global_load_lds_dwordx4 v[168:169], off
	v_lshl_add_u64 v[168:169], s[46:47], 0, v[164:165]
	s_add_i32 m0, s34, 0xe000
	s_nop 0
	global_load_lds_dwordx4 v[168:169], off
	s_waitcnt vmcnt(8)
	s_waitcnt lgkmcnt(0)
	s_setprio 1
	s_barrier
	v_mfma_f32_16x16x32_bf16 v[130:133], v[124:127], v[182:185], v[130:133]
	v_mfma_f32_16x16x32_bf16 v[130:133], v[134:137], v[186:189], v[130:133]
	v_mfma_f32_16x16x32_bf16 v[120:123], v[142:145], v[186:189], v[120:123]
	v_mfma_f32_16x16x32_bf16 v[120:123], v[138:141], v[182:185], v[120:123]
	v_mfma_f32_16x16x32_bf16 v[116:119], v[146:149], v[182:185], v[116:119]
	v_mfma_f32_16x16x32_bf16 v[116:119], v[150:153], v[186:189], v[116:119]
	v_mfma_f32_16x16x32_bf16 v[112:115], v[158:161], v[186:189], v[112:115]
	v_mfma_f32_16x16x32_bf16 v[112:115], v[154:157], v[182:185], v[112:115]
	v_mfma_f32_16x16x32_bf16 v[96:99], v[154:157], v[190:193], v[96:99]
	v_mfma_f32_16x16x32_bf16 v[96:99], v[158:161], v[200:203], v[96:99]
	v_mfma_f32_16x16x32_bf16 v[100:103], v[150:153], v[200:203], v[100:103]
	v_mfma_f32_16x16x32_bf16 v[100:103], v[146:149], v[190:193], v[100:103]
	v_mfma_f32_16x16x32_bf16 v[104:107], v[138:141], v[190:193], v[104:107]
	v_mfma_f32_16x16x32_bf16 v[104:107], v[142:145], v[200:203], v[104:107]
	v_mfma_f32_16x16x32_bf16 v[108:111], v[134:137], v[200:203], v[108:111]
	v_mfma_f32_16x16x32_bf16 v[108:111], v[124:127], v[190:193], v[108:111]
	v_mfma_f32_16x16x32_bf16 v[92:95], v[124:127], v[204:207], v[92:95]
	v_mfma_f32_16x16x32_bf16 v[92:95], v[134:137], v[210:213], v[92:95]
	v_mfma_f32_16x16x32_bf16 v[88:91], v[142:145], v[210:213], v[88:91]
	v_mfma_f32_16x16x32_bf16 v[88:91], v[138:141], v[204:207], v[88:91]
	v_mfma_f32_16x16x32_bf16 v[84:87], v[146:149], v[204:207], v[84:87]
	v_mfma_f32_16x16x32_bf16 v[84:87], v[150:153], v[210:213], v[84:87]
	v_mfma_f32_16x16x32_bf16 v[80:83], v[158:161], v[210:213], v[80:83]
	v_mfma_f32_16x16x32_bf16 v[80:83], v[154:157], v[204:207], v[80:83]
	v_mfma_f32_16x16x32_bf16 v[64:67], v[154:157], v[226:229], v[64:67]
	v_mfma_f32_16x16x32_bf16 v[64:67], v[158:161], v[230:233], v[64:67]
	v_mfma_f32_16x16x32_bf16 v[68:71], v[150:153], v[230:233], v[68:71]
	v_mfma_f32_16x16x32_bf16 v[68:71], v[146:149], v[226:229], v[68:71]
	v_mfma_f32_16x16x32_bf16 v[72:75], v[138:141], v[226:229], v[72:75]
	v_mfma_f32_16x16x32_bf16 v[72:75], v[142:145], v[230:233], v[72:75]
	v_mfma_f32_16x16x32_bf16 v[76:79], v[134:137], v[230:233], v[76:79]
	v_mfma_f32_16x16x32_bf16 v[76:79], v[124:127], v[226:229], v[76:79]
	s_barrier
	s_setprio 0
	s_add_i32 s44, s51, s31
	v_lshl_add_u64 v[168:169], s[20:21], 0, v[128:129]
	s_mov_b32 m0, s44
	ds_read_b128 v[182:185], v197 offset:16384
	ds_read_b128 v[186:189], v197 offset:17408
	ds_read_b128 v[190:193], v197 offset:18432
	ds_read_b128 v[200:203], v197 offset:19456
	ds_read_b128 v[204:207], v197 offset:20480
	ds_read_b128 v[210:213], v197 offset:21504
	ds_read_b128 v[226:229], v197 offset:22528
	ds_read_b128 v[230:233], v197 offset:23552
	global_load_lds_dwordx4 v[168:169], off
	s_add_i32 m0, s44, 0x2000
	s_add_u32 s46, s20, 0x200000
	v_lshl_add_u64 v[214:215], s[20:21], 0, v[162:163]
	s_addc_u32 s47, s21, 0
	s_add_i32 s44, s53, s31
	global_load_lds_dwordx4 v[214:215], off
	v_lshl_add_u64 v[234:235], s[46:47], 0, v[128:129]
	s_mov_b32 m0, s44
	v_lshl_add_u64 v[236:237], s[26:27], 0, v[164:165]
	global_load_lds_dwordx4 v[234:235], off
	v_lshl_add_u64 v[234:235], s[46:47], 0, v[162:163]
	s_add_i32 m0, s44, 0x2000
	s_nop 0
	global_load_lds_dwordx4 v[234:235], off
	v_lshl_add_u64 v[234:235], s[26:27], 0, v[166:167]
	s_mov_b32 m0, s34
	s_nop 0
	global_load_lds_dwordx4 v[234:235], off
	s_mov_b32 m0, s35
	s_nop 0
	global_load_lds_dwordx4 v[236:237], off
	s_waitcnt vmcnt(8)
	s_waitcnt lgkmcnt(0)
	s_setprio 1
	s_barrier
; #define PG8_STAGE(bufoff, gbase, voff) do { _Pragma("unroll") for (int _i = 0; _i < 2; ++_i) \
;         __builtin_amdgcn_global_load_lds((const unsigned*)((const char*)(gbase) + (voff)[_i]), (PG8_LAS unsigned*)(lds + (bufoff) + ldsw + _i * 8192), 16, 0, 0); } while (0)
; #define PG8_LDA(dst, b, h) do { _Pragma("unroll") for (int m = 0; m < 4; ++m) _Pragma("unroll") for (int k = 0; k < 2; ++k) dst[m][k] = *(const PG8_LAS bf16x8*)(lds + PG8_SA(b, h) + aoff + m * 2048 + k * 1024); } while (0)
; #define PG8_LDB(dst, b, h) do { _Pragma("unroll") for (int n = 0; n < 2; ++n) _Pragma("unroll") for (int k = 0; k < 2; ++k) dst[n][k] = *(const PG8_LAS bf16x8*)(lds + PG8_SB(b, h) + boff + n * 2048 + k * 1024); } while (0)
; #define PG8_MMA(ai, bj, At, Bt) do { __builtin_amdgcn_s_setprio(1); _Pragma("unroll") for (int m = 0; m < 4; ++m) _Pragma("unroll") for (int n = 0; n < 2; ++n) _Pragma("unroll") for (int k = 0; k < 2; ++k) \
;         acc[ai][bj][m][n] = __builtin_amdgcn_mfma_f32_16x16x32_bf16(Bt[n][k], At[m][k], acc[ai][bj][m][n], 0, 0, 0); __builtin_amdgcn_s_setprio(0); } while (0)
; #define PG8_WAIT_V(n) asm volatile("s_waitcnt vmcnt(" #n ")" ::: "memory")
; #define PG8_WAIT_L(n) asm volatile("s_waitcnt lgkmcnt(" #n ")" ::: "memory")
; #define PG8_BAR __builtin_amdgcn_s_barrier()
; #define PG8_SCHED __builtin_amdgcn_sched_barrier(0)
; template <class Epi, class Sched, bool ALIGN_EPI = false, bool SP2 = false, class Hook = NoHook, bool REVK = false>
; __device__ __forceinline__ void gemm_phase(PG8_LAS unsigned char* lds, const Gemm g, const Sched& S, const Epi& E, const Hook H = Hook()) {
;     ...
;             PG8_WAIT_V(8); PG8_WAIT_L(0); PG8_BAR; PG8_MMA(1, 0, At, B0); PG8_MMA(1, 1, At, B1); PG8_BAR; PG8_SCHED;
;             PG8_LDB(B0, 1, 0); PG8_LDB(B1, 1, 1); PG8_SCHED; PG8_LDA(At, 1, 0); PG8_STAGE(PG8_SA(0, 1), a2 + hstep, voffA);
;             PG8_WAIT_V(8); PG8_WAIT_L(0); PG8_BAR; PG8_MMA(0, 0, At, B0); PG8_MMA(0, 1, At, B1); PG8_BAR; PG8_SCHED;
	v_mfma_f32_16x16x32_bf16 v[60:63], v[124:127], v[182:185], v[60:63]
	v_mfma_f32_16x16x32_bf16 v[60:63], v[134:137], v[186:189], v[60:63]
	v_mfma_f32_16x16x32_bf16 v[56:59], v[142:145], v[186:189], v[56:59]
	v_mfma_f32_16x16x32_bf16 v[56:59], v[138:141], v[182:185], v[56:59]
	v_mfma_f32_16x16x32_bf16 v[52:55], v[146:149], v[182:185], v[52:55]
	v_mfma_f32_16x16x32_bf16 v[52:55], v[150:153], v[186:189], v[52:55]
	v_mfma_f32_16x16x32_bf16 v[48:51], v[158:161], v[186:189], v[48:51]
	v_mfma_f32_16x16x32_bf16 v[48:51], v[154:157], v[182:185], v[48:51]
	v_mfma_f32_16x16x32_bf16 v[32:35], v[154:157], v[190:193], v[32:35]
	v_mfma_f32_16x16x32_bf16 v[32:35], v[158:161], v[200:203], v[32:35]
	v_mfma_f32_16x16x32_bf16 v[36:39], v[150:153], v[200:203], v[36:39]
	v_mfma_f32_16x16x32_bf16 v[36:39], v[146:149], v[190:193], v[36:39]
	v_mfma_f32_16x16x32_bf16 v[40:43], v[138:141], v[190:193], v[40:43]
	v_mfma_f32_16x16x32_bf16 v[40:43], v[142:145], v[200:203], v[40:43]
	v_mfma_f32_16x16x32_bf16 v[44:47], v[134:137], v[200:203], v[44:47]
	v_mfma_f32_16x16x32_bf16 v[44:47], v[124:127], v[190:193], v[44:47]
	v_mfma_f32_16x16x32_bf16 v[28:31], v[124:127], v[204:207], v[28:31]
	v_mfma_f32_16x16x32_bf16 v[28:31], v[134:137], v[210:213], v[28:31]
	v_mfma_f32_16x16x32_bf16 v[24:27], v[142:145], v[210:213], v[24:27]
	v_mfma_f32_16x16x32_bf16 v[24:27], v[138:141], v[204:207], v[24:27]
	v_mfma_f32_16x16x32_bf16 v[20:23], v[146:149], v[204:207], v[20:23]
	v_mfma_f32_16x16x32_bf16 v[20:23], v[150:153], v[210:213], v[20:23]
	v_mfma_f32_16x16x32_bf16 v[16:19], v[158:161], v[210:213], v[16:19]
	v_mfma_f32_16x16x32_bf16 v[16:19], v[154:157], v[204:207], v[16:19]
	v_mfma_f32_16x16x32_bf16 v[0:3], v[154:157], v[226:229], v[0:3]
	v_mfma_f32_16x16x32_bf16 v[0:3], v[158:161], v[230:233], v[0:3]
	v_mfma_f32_16x16x32_bf16 v[4:7], v[150:153], v[230:233], v[4:7]
	v_mfma_f32_16x16x32_bf16 v[4:7], v[146:149], v[226:229], v[4:7]
	v_mfma_f32_16x16x32_bf16 v[8:11], v[138:141], v[226:229], v[8:11]
	v_mfma_f32_16x16x32_bf16 v[8:11], v[142:145], v[230:233], v[8:11]
	v_mfma_f32_16x16x32_bf16 v[12:15], v[134:137], v[230:233], v[12:15]
	v_mfma_f32_16x16x32_bf16 v[12:15], v[124:127], v[226:229], v[12:15]
	s_barrier
	s_setprio 0
	s_add_i32 s44, 0, 0x18000
	s_add_i32 s46, 0, 0x1c000
	v_add_u32_e32 v142, s44, v195
	v_add_u32_e32 v158, s46, v195
	ds_read_b128 v[124:127], v142
	ds_read_b128 v[134:137], v142 offset:1024
	ds_read_b128 v[138:141], v142 offset:2048
	ds_read_b128 v[142:145], v142 offset:3072
	ds_read_b128 v[146:149], v158
	ds_read_b128 v[150:153], v158 offset:1024
	ds_read_b128 v[154:157], v158 offset:2048
	ds_read_b128 v[158:161], v158 offset:3072
	s_add_u32 s26, s26, 0x200000
	s_addc_u32 s27, s27, 0
	s_mov_b32 m0, s36
	v_lshl_add_u64 v[238:239], s[26:27], 0, v[166:167]
	ds_read_b128 v[182:185], v197 offset:32768
	ds_read_b128 v[186:189], v197 offset:33792
	ds_read_b128 v[190:193], v197 offset:34816
	ds_read_b128 v[200:203], v197 offset:35840
	ds_read_b128 v[204:207], v197 offset:36864
	ds_read_b128 v[210:213], v197 offset:37888
	ds_read_b128 v[226:229], v197 offset:38912
	ds_read_b128 v[230:233], v197 offset:39936
	global_load_lds_dwordx4 v[238:239], off
	v_lshl_add_u64 v[238:239], s[26:27], 0, v[164:165]
	s_mov_b32 m0, s38
	s_nop 0
	global_load_lds_dwordx4 v[238:239], off
	s_waitcnt vmcnt(8)
	s_waitcnt lgkmcnt(0)
	s_setprio 1
	s_barrier
	v_mfma_f32_16x16x32_bf16 v[130:133], v[124:127], v[182:185], v[130:133]
	v_mfma_f32_16x16x32_bf16 v[130:133], v[134:137], v[186:189], v[130:133]
	v_mfma_f32_16x16x32_bf16 v[120:123], v[142:145], v[186:189], v[120:123]
	v_mfma_f32_16x16x32_bf16 v[120:123], v[138:141], v[182:185], v[120:123]
	v_mfma_f32_16x16x32_bf16 v[116:119], v[146:149], v[182:185], v[116:119]
	v_mfma_f32_16x16x32_bf16 v[116:119], v[150:153], v[186:189], v[116:119]
	v_mfma_f32_16x16x32_bf16 v[112:115], v[158:161], v[186:189], v[112:115]
	v_mfma_f32_16x16x32_bf16 v[112:115], v[154:157], v[182:185], v[112:115]
	v_mfma_f32_16x16x32_bf16 v[96:99], v[154:157], v[190:193], v[96:99]
	v_mfma_f32_16x16x32_bf16 v[96:99], v[158:161], v[200:203], v[96:99]
	v_mfma_f32_16x16x32_bf16 v[100:103], v[150:153], v[200:203], v[100:103]
	v_mfma_f32_16x16x32_bf16 v[100:103], v[146:149], v[190:193], v[100:103]
	v_mfma_f32_16x16x32_bf16 v[104:107], v[138:141], v[190:193], v[104:107]
	v_mfma_f32_16x16x32_bf16 v[104:107], v[142:145], v[200:203], v[104:107]
	v_mfma_f32_16x16x32_bf16 v[108:111], v[134:137], v[200:203], v[108:111]
	v_mfma_f32_16x16x32_bf16 v[108:111], v[124:127], v[190:193], v[108:111]
	v_mfma_f32_16x16x32_bf16 v[92:95], v[124:127], v[204:207], v[92:95]
	v_mfma_f32_16x16x32_bf16 v[92:95], v[134:137], v[210:213], v[92:95]
	v_mfma_f32_16x16x32_bf16 v[88:91], v[142:145], v[210:213], v[88:91]
	v_mfma_f32_16x16x32_bf16 v[88:91], v[138:141], v[204:207], v[88:91]
	v_mfma_f32_16x16x32_bf16 v[84:87], v[146:149], v[204:207], v[84:87]
	v_mfma_f32_16x16x32_bf16 v[84:87], v[150:153], v[210:213], v[84:87]
	v_mfma_f32_16x16x32_bf16 v[80:83], v[158:161], v[210:213], v[80:83]
	v_mfma_f32_16x16x32_bf16 v[80:83], v[154:157], v[204:207], v[80:83]
	v_mfma_f32_16x16x32_bf16 v[64:67], v[154:157], v[226:229], v[64:67]
	v_mfma_f32_16x16x32_bf16 v[64:67], v[158:161], v[230:233], v[64:67]
	v_mfma_f32_16x16x32_bf16 v[68:71], v[150:153], v[230:233], v[68:71]
	v_mfma_f32_16x16x32_bf16 v[68:71], v[146:149], v[226:229], v[68:71]
	v_mfma_f32_16x16x32_bf16 v[72:75], v[138:141], v[226:229], v[72:75]
	v_mfma_f32_16x16x32_bf16 v[72:75], v[142:145], v[230:233], v[72:75]
	v_mfma_f32_16x16x32_bf16 v[76:79], v[134:137], v[230:233], v[76:79]
	v_mfma_f32_16x16x32_bf16 v[76:79], v[124:127], v[226:229], v[76:79]
	s_barrier
; #define PG8_STAGE(bufoff, gbase, voff) do { _Pragma("unroll") for (int _i = 0; _i < 2; ++_i) \
;         __builtin_amdgcn_global_load_lds((const unsigned*)((const char*)(gbase) + (voff)[_i]), (PG8_LAS unsigned*)(lds + (bufoff) + ldsw + _i * 8192), 16, 0, 0); } while (0)
; #define PG8_LDA(dst, b, h) do { _Pragma("unroll") for (int m = 0; m < 4; ++m) _Pragma("unroll") for (int k = 0; k < 2; ++k) dst[m][k] = *(const PG8_LAS bf16x8*)(lds + PG8_SA(b, h) + aoff + m * 2048 + k * 1024); } while (0)
; #define PG8_MMA(ai, bj, At, Bt) do { __builtin_amdgcn_s_setprio(1); _Pragma("unroll") for (int m = 0; m < 4; ++m) _Pragma("unroll") for (int n = 0; n < 2; ++n) _Pragma("unroll") for (int k = 0; k < 2; ++k) \
;         acc[ai][bj][m][n] = __builtin_amdgcn_mfma_f32_16x16x32_bf16(Bt[n][k], At[m][k], acc[ai][bj][m][n], 0, 0, 0); __builtin_amdgcn_s_setprio(0); } while (0)
; #define PG8_WAIT_V(n) asm volatile("s_waitcnt vmcnt(" #n ")" ::: "memory")
; #define PG8_WAIT_L(n) asm volatile("s_waitcnt lgkmcnt(" #n ")" ::: "memory")
; #define PG8_BAR __builtin_amdgcn_s_barrier()
; #define PG8_SCHED __builtin_amdgcn_sched_barrier(0)
; template <class Epi, class Sched, bool ALIGN_EPI = false, bool SP2 = false, class Hook = NoHook, bool REVK = false>
; __device__ __forceinline__ void gemm_phase(PG8_LAS unsigned char* lds, const Gemm g, const Sched& S, const Epi& E, const Hook H = Hook()) {
;     ...
;             PG8_LDA(At, 1, 1); PG8_STAGE(PG8_SB(1, 0), b3, voffB); PG8_STAGE(PG8_SB(1, 1), b3 + hstep, voffB); PG8_STAGE(PG8_SA(1, 0), a3, voffA);
;             PG8_WAIT_V(8); PG8_WAIT_L(0); PG8_BAR; PG8_MMA(1, 0, At, B0); PG8_MMA(1, 1, At, B1); PG8_BAR; PG8_SCHED;
	s_setprio 0
	s_add_i32 s26, s44, s31
	v_lshl_add_u64 v[168:169], v[168:169], 0, s[70:71]
	s_mov_b32 m0, s26
	ds_read_b128 v[182:185], v197 offset:49152
	ds_read_b128 v[186:189], v197 offset:50176
	ds_read_b128 v[190:193], v197 offset:51200
	ds_read_b128 v[200:203], v197 offset:52224
	ds_read_b128 v[204:207], v197 offset:53248
	ds_read_b128 v[210:213], v197 offset:54272
	ds_read_b128 v[226:229], v197 offset:55296
	ds_read_b128 v[230:233], v197 offset:56320
	global_load_lds_dwordx4 v[168:169], off
	s_add_i32 m0, s26, 0x2000
	s_add_u32 s20, s20, 0x1fff80
	v_lshl_add_u64 v[168:169], v[214:215], 0, s[70:71]
	s_addc_u32 s21, s21, 0
	s_add_i32 s26, s46, s31
	global_load_lds_dwordx4 v[168:169], off
	v_lshl_add_u64 v[168:169], s[20:21], 0, v[128:129]
	s_mov_b32 m0, s26
	s_nop 0
	global_load_lds_dwordx4 v[168:169], off
	v_lshl_add_u64 v[168:169], s[20:21], 0, v[162:163]
	s_add_i32 m0, s26, 0x2000
	s_nop 0
	global_load_lds_dwordx4 v[168:169], off
	v_lshl_add_u64 v[168:169], v[234:235], 0, s[70:71]
	s_mov_b32 m0, s39
	s_nop 0
	global_load_lds_dwordx4 v[168:169], off
	v_lshl_add_u64 v[168:169], v[236:237], 0, s[70:71]
	s_mov_b32 m0, s40
	s_nop 0
	global_load_lds_dwordx4 v[168:169], off
	s_waitcnt vmcnt(8)
	s_waitcnt lgkmcnt(0)
	s_setprio 1
	s_barrier
	v_mfma_f32_16x16x32_bf16 v[60:63], v[124:127], v[182:185], v[60:63]
	v_mfma_f32_16x16x32_bf16 v[60:63], v[134:137], v[186:189], v[60:63]
	v_mfma_f32_16x16x32_bf16 v[56:59], v[142:145], v[186:189], v[56:59]
	v_mfma_f32_16x16x32_bf16 v[56:59], v[138:141], v[182:185], v[56:59]
	v_mfma_f32_16x16x32_bf16 v[52:55], v[146:149], v[182:185], v[52:55]
	v_mfma_f32_16x16x32_bf16 v[52:55], v[150:153], v[186:189], v[52:55]
	v_mfma_f32_16x16x32_bf16 v[48:51], v[158:161], v[186:189], v[48:51]
	v_mfma_f32_16x16x32_bf16 v[48:51], v[154:157], v[182:185], v[48:51]
	v_mfma_f32_16x16x32_bf16 v[32:35], v[154:157], v[190:193], v[32:35]
	v_mfma_f32_16x16x32_bf16 v[32:35], v[158:161], v[200:203], v[32:35]
	v_mfma_f32_16x16x32_bf16 v[36:39], v[150:153], v[200:203], v[36:39]
	v_mfma_f32_16x16x32_bf16 v[36:39], v[146:149], v[190:193], v[36:39]
	v_mfma_f32_16x16x32_bf16 v[40:43], v[138:141], v[190:193], v[40:43]
	v_mfma_f32_16x16x32_bf16 v[40:43], v[142:145], v[200:203], v[40:43]
	v_mfma_f32_16x16x32_bf16 v[44:47], v[134:137], v[200:203], v[44:47]
	v_mfma_f32_16x16x32_bf16 v[44:47], v[124:127], v[190:193], v[44:47]
	v_mfma_f32_16x16x32_bf16 v[28:31], v[124:127], v[204:207], v[28:31]
	v_mfma_f32_16x16x32_bf16 v[28:31], v[134:137], v[210:213], v[28:31]
	v_mfma_f32_16x16x32_bf16 v[24:27], v[142:145], v[210:213], v[24:27]
	v_mfma_f32_16x16x32_bf16 v[24:27], v[138:141], v[204:207], v[24:27]
	v_mfma_f32_16x16x32_bf16 v[20:23], v[146:149], v[204:207], v[20:23]
	v_mfma_f32_16x16x32_bf16 v[20:23], v[150:153], v[210:213], v[20:23]
	v_mfma_f32_16x16x32_bf16 v[16:19], v[158:161], v[210:213], v[16:19]
	v_mfma_f32_16x16x32_bf16 v[16:19], v[154:157], v[204:207], v[16:19]
	v_mfma_f32_16x16x32_bf16 v[0:3], v[154:157], v[226:229], v[0:3]
	v_mfma_f32_16x16x32_bf16 v[0:3], v[158:161], v[230:233], v[0:3]
	v_mfma_f32_16x16x32_bf16 v[4:7], v[150:153], v[230:233], v[4:7]
	v_mfma_f32_16x16x32_bf16 v[4:7], v[146:149], v[226:229], v[4:7]
	v_mfma_f32_16x16x32_bf16 v[8:11], v[138:141], v[226:229], v[8:11]
	v_mfma_f32_16x16x32_bf16 v[8:11], v[142:145], v[230:233], v[8:11]
	v_mfma_f32_16x16x32_bf16 v[12:15], v[134:137], v[230:233], v[12:15]
	v_mfma_f32_16x16x32_bf16 v[12:15], v[124:127], v[226:229], v[12:15]
	s_barrier
	s_setprio 0
	s_cmpk_gt_u32 s42, 0x7d
	s_mov_b32 s42, s43
	s_cbranch_scc1 .LBB0_659
